# ph_pre triangular inverse restructured as blocked f32 inverse (two 32x32 diagonal blocks on the half-waves, then two dense 32x32x32 f32 products) instead of 64-row serial substitution
# speedup vs baseline: 1.0815x; 1.0230x over previous
.LBB0_281:
.LBB0_282:
	s_andn2_saveexec_b64 s[44:45], s[2:3]
	s_cbranch_execz .LBB0_296
	v_cndmask_b32_e64 v194, v244, v245, s[38:39]
	v_mov_b32_e32 v200, 0
	v_mov_b32_e32 v201, 0
	v_mov_b32_e32 v203, 0
	v_mul_u32_u24_e32 v204, 0x2280, v189
	v_add_u32_e32 v195, v194, v204
	v_mul_u32_u24_e32 v204, 0x1100, v189
	v_add_u32_e32 v204, 0x2200, v204
	v_add_u32_e32 v196, v194, v204
	s_cmp_lg_u32 s87, 0
	s_cselect_b32 s0, 0x2000, 0
	s_add_u32 s0, s0, 0x1e800
	v_lshlrev_b32_e32 v199, 2, v188
	v_lshl_add_u32 v197, v189, 11, s0
	v_sub_u32_e32 v204, 1, v189
	v_lshl_add_u32 v204, v204, 12, s0
	v_add_u32_e32 v198, v204, v199
	ds_read_b128 v[80:83], v195 offset:272
	v_cmp_eq_u32_e32 vcc, 0, v188
	s_nop 1
	v_cndmask_b32_e64 v0, 0, 1.0, vcc
	v_cmp_eq_u32_e32 vcc, 1, v188
	s_nop 1
	v_cndmask_b32_e64 v202, 0, 1.0, vcc
	s_waitcnt lgkmcnt(0)
	v_fma_f32 v146, -v0, v80, v202
	ds_read_b128 v[80:83], v195 offset:544
	v_mov_b32_e32 v1, v146
	v_cmp_eq_u32_e32 vcc, 2, v188
	s_nop 1
	v_cndmask_b32_e64 v202, 0, 1.0, vcc
	s_waitcnt lgkmcnt(0)
	v_pk_fma_f32 v[146:147], v[0:1], v[80:81], v[202:203] neg_lo:[1,0,0] neg_hi:[1,0,0]
	ds_read_b128 v[80:83], v195 offset:816
	v_add_f32_e32 v2, v146, v147
	v_cmp_eq_u32_e32 vcc, 3, v188
	s_nop 1
	v_cndmask_b32_e64 v202, 0, 1.0, vcc
	s_waitcnt lgkmcnt(0)
	v_pk_fma_f32 v[146:147], v[0:1], v[80:81], v[202:203] neg_lo:[1,0,0] neg_hi:[1,0,0]
	v_fma_f32 v148, -v2, v82, v200
	ds_read_b128 v[80:83], v195 offset:1088
	v_add_f32_e32 v150, v146, v147
	v_add_f32_e32 v3, v148, v150
	v_cmp_eq_u32_e32 vcc, 4, v188
	s_nop 1
	v_cndmask_b32_e64 v202, 0, 1.0, vcc
	s_waitcnt lgkmcnt(0)
	v_pk_fma_f32 v[146:147], v[0:1], v[80:81], v[202:203] neg_lo:[1,0,0] neg_hi:[1,0,0]
	v_pk_fma_f32 v[148:149], v[2:3], v[82:83], v[200:201] neg_lo:[1,0,0] neg_hi:[1,0,0]
	ds_read_b128 v[80:83], v195 offset:1360
	ds_read_b128 v[84:87], v195 offset:1376
	v_add_f32_e32 v150, v147, v146
	v_add_f32_e32 v151, v148, v149
	v_add_f32_e32 v4, v151, v150
	v_cmp_eq_u32_e32 vcc, 5, v188
	s_nop 1
	v_cndmask_b32_e64 v202, 0, 1.0, vcc
	s_waitcnt lgkmcnt(0)
	v_pk_fma_f32 v[146:147], v[0:1], v[80:81], v[202:203] neg_lo:[1,0,0] neg_hi:[1,0,0]
	v_pk_fma_f32 v[148:149], v[2:3], v[82:83], v[200:201] neg_lo:[1,0,0] neg_hi:[1,0,0]
	ds_read_b128 v[80:83], v195 offset:1632
	v_fma_f32 v146, -v4, v84, v146
	ds_read_b128 v[84:87], v195 offset:1648
	v_add_f32_e32 v150, v147, v146
	v_add_f32_e32 v151, v148, v149
	v_add_f32_e32 v5, v151, v150
	v_cmp_eq_u32_e32 vcc, 6, v188
	s_nop 1
	v_cndmask_b32_e64 v202, 0, 1.0, vcc
	s_waitcnt lgkmcnt(0)
	v_pk_fma_f32 v[146:147], v[0:1], v[80:81], v[202:203] neg_lo:[1,0,0] neg_hi:[1,0,0]
	v_pk_fma_f32 v[148:149], v[2:3], v[82:83], v[200:201] neg_lo:[1,0,0] neg_hi:[1,0,0]
	ds_read_b128 v[80:83], v195 offset:1904
	v_pk_fma_f32 v[146:147], v[4:5], v[84:85], v[146:147] neg_lo:[1,0,0] neg_hi:[1,0,0]
	ds_read_b128 v[84:87], v195 offset:1920
	v_add_f32_e32 v150, v147, v146
	v_add_f32_e32 v151, v148, v149
	v_add_f32_e32 v6, v151, v150
	v_cmp_eq_u32_e32 vcc, 7, v188
	s_nop 1
	v_cndmask_b32_e64 v202, 0, 1.0, vcc
	s_waitcnt lgkmcnt(0)
	v_pk_fma_f32 v[146:147], v[0:1], v[80:81], v[202:203] neg_lo:[1,0,0] neg_hi:[1,0,0]
	v_pk_fma_f32 v[148:149], v[2:3], v[82:83], v[200:201] neg_lo:[1,0,0] neg_hi:[1,0,0]
	ds_read_b128 v[80:83], v195 offset:2176
	v_pk_fma_f32 v[146:147], v[4:5], v[84:85], v[146:147] neg_lo:[1,0,0] neg_hi:[1,0,0]
	v_fma_f32 v148, -v6, v86, v148
	ds_read_b128 v[84:87], v195 offset:2192
	v_add_f32_e32 v150, v147, v146
	v_add_f32_e32 v151, v148, v149
	v_add_f32_e32 v7, v151, v150
	v_cmp_eq_u32_e32 vcc, 8, v188
	s_nop 1
	v_cndmask_b32_e64 v202, 0, 1.0, vcc
	s_waitcnt lgkmcnt(0)
	v_pk_fma_f32 v[146:147], v[0:1], v[80:81], v[202:203] neg_lo:[1,0,0] neg_hi:[1,0,0]
	v_pk_fma_f32 v[148:149], v[2:3], v[82:83], v[200:201] neg_lo:[1,0,0] neg_hi:[1,0,0]
	ds_read_b128 v[80:83], v195 offset:2448
	v_pk_fma_f32 v[146:147], v[4:5], v[84:85], v[146:147] neg_lo:[1,0,0] neg_hi:[1,0,0]
	v_pk_fma_f32 v[148:149], v[6:7], v[86:87], v[148:149] neg_lo:[1,0,0] neg_hi:[1,0,0]
	ds_read_b128 v[84:87], v195 offset:2464
	ds_read_b128 v[88:91], v195 offset:2480
	v_add_f32_e32 v150, v147, v146
	v_add_f32_e32 v151, v148, v149
	v_add_f32_e32 v8, v151, v150
	v_cmp_eq_u32_e32 vcc, 9, v188
	s_nop 1
	v_cndmask_b32_e64 v202, 0, 1.0, vcc
	s_waitcnt lgkmcnt(0)
	v_pk_fma_f32 v[146:147], v[0:1], v[80:81], v[202:203] neg_lo:[1,0,0] neg_hi:[1,0,0]
	v_pk_fma_f32 v[148:149], v[2:3], v[82:83], v[200:201] neg_lo:[1,0,0] neg_hi:[1,0,0]
	ds_read_b128 v[80:83], v195 offset:2720
	v_pk_fma_f32 v[146:147], v[4:5], v[84:85], v[146:147] neg_lo:[1,0,0] neg_hi:[1,0,0]
	v_pk_fma_f32 v[148:149], v[6:7], v[86:87], v[148:149] neg_lo:[1,0,0] neg_hi:[1,0,0]
	ds_read_b128 v[84:87], v195 offset:2736
	v_fma_f32 v146, -v8, v88, v146
	ds_read_b128 v[88:91], v195 offset:2752
	v_add_f32_e32 v150, v147, v146
	v_add_f32_e32 v151, v148, v149
	v_add_f32_e32 v9, v151, v150
	v_cmp_eq_u32_e32 vcc, 10, v188
	s_nop 1
	v_cndmask_b32_e64 v202, 0, 1.0, vcc
	s_waitcnt lgkmcnt(0)
	v_pk_fma_f32 v[146:147], v[0:1], v[80:81], v[202:203] neg_lo:[1,0,0] neg_hi:[1,0,0]
	v_pk_fma_f32 v[148:149], v[2:3], v[82:83], v[200:201] neg_lo:[1,0,0] neg_hi:[1,0,0]
	ds_read_b128 v[80:83], v195 offset:2992
	v_pk_fma_f32 v[146:147], v[4:5], v[84:85], v[146:147] neg_lo:[1,0,0] neg_hi:[1,0,0]
	v_pk_fma_f32 v[148:149], v[6:7], v[86:87], v[148:149] neg_lo:[1,0,0] neg_hi:[1,0,0]
	ds_read_b128 v[84:87], v195 offset:3008
	v_pk_fma_f32 v[146:147], v[8:9], v[88:89], v[146:147] neg_lo:[1,0,0] neg_hi:[1,0,0]
	ds_read_b128 v[88:91], v195 offset:3024
	v_add_f32_e32 v150, v147, v146
	v_add_f32_e32 v151, v148, v149
	v_add_f32_e32 v10, v151, v150
	v_cmp_eq_u32_e32 vcc, 11, v188
	s_nop 1
	v_cndmask_b32_e64 v202, 0, 1.0, vcc
	s_waitcnt lgkmcnt(0)
	v_pk_fma_f32 v[146:147], v[0:1], v[80:81], v[202:203] neg_lo:[1,0,0] neg_hi:[1,0,0]
	v_pk_fma_f32 v[148:149], v[2:3], v[82:83], v[200:201] neg_lo:[1,0,0] neg_hi:[1,0,0]
	ds_read_b128 v[80:83], v195 offset:3264
	v_pk_fma_f32 v[146:147], v[4:5], v[84:85], v[146:147] neg_lo:[1,0,0] neg_hi:[1,0,0]
	v_pk_fma_f32 v[148:149], v[6:7], v[86:87], v[148:149] neg_lo:[1,0,0] neg_hi:[1,0,0]
	ds_read_b128 v[84:87], v195 offset:3280
	v_pk_fma_f32 v[146:147], v[8:9], v[88:89], v[146:147] neg_lo:[1,0,0] neg_hi:[1,0,0]
	v_fma_f32 v148, -v10, v90, v148
	ds_read_b128 v[88:91], v195 offset:3296
	v_add_f32_e32 v150, v147, v146
	v_add_f32_e32 v151, v148, v149
	v_add_f32_e32 v11, v151, v150
	v_cmp_eq_u32_e32 vcc, 12, v188
	s_nop 1
	v_cndmask_b32_e64 v202, 0, 1.0, vcc
	s_waitcnt lgkmcnt(0)
	v_pk_fma_f32 v[146:147], v[0:1], v[80:81], v[202:203] neg_lo:[1,0,0] neg_hi:[1,0,0]
	v_pk_fma_f32 v[148:149], v[2:3], v[82:83], v[200:201] neg_lo:[1,0,0] neg_hi:[1,0,0]
	ds_read_b128 v[80:83], v195 offset:3536
	v_pk_fma_f32 v[146:147], v[4:5], v[84:85], v[146:147] neg_lo:[1,0,0] neg_hi:[1,0,0]
	v_pk_fma_f32 v[148:149], v[6:7], v[86:87], v[148:149] neg_lo:[1,0,0] neg_hi:[1,0,0]
	ds_read_b128 v[84:87], v195 offset:3552
	v_pk_fma_f32 v[146:147], v[8:9], v[88:89], v[146:147] neg_lo:[1,0,0] neg_hi:[1,0,0]
	v_pk_fma_f32 v[148:149], v[10:11], v[90:91], v[148:149] neg_lo:[1,0,0] neg_hi:[1,0,0]
	ds_read_b128 v[88:91], v195 offset:3568
	ds_read_b128 v[92:95], v195 offset:3584
	v_add_f32_e32 v150, v147, v146
	v_add_f32_e32 v151, v148, v149
	v_add_f32_e32 v12, v151, v150
	v_cmp_eq_u32_e32 vcc, 13, v188
	s_nop 1
	v_cndmask_b32_e64 v202, 0, 1.0, vcc
	s_waitcnt lgkmcnt(0)
	v_pk_fma_f32 v[146:147], v[0:1], v[80:81], v[202:203] neg_lo:[1,0,0] neg_hi:[1,0,0]
	v_pk_fma_f32 v[148:149], v[2:3], v[82:83], v[200:201] neg_lo:[1,0,0] neg_hi:[1,0,0]
	ds_read_b128 v[80:83], v195 offset:3808
	v_pk_fma_f32 v[146:147], v[4:5], v[84:85], v[146:147] neg_lo:[1,0,0] neg_hi:[1,0,0]
	v_pk_fma_f32 v[148:149], v[6:7], v[86:87], v[148:149] neg_lo:[1,0,0] neg_hi:[1,0,0]
	ds_read_b128 v[84:87], v195 offset:3824
	v_pk_fma_f32 v[146:147], v[8:9], v[88:89], v[146:147] neg_lo:[1,0,0] neg_hi:[1,0,0]
	v_pk_fma_f32 v[148:149], v[10:11], v[90:91], v[148:149] neg_lo:[1,0,0] neg_hi:[1,0,0]
	ds_read_b128 v[88:91], v195 offset:3840
	v_fma_f32 v146, -v12, v92, v146
	ds_read_b128 v[92:95], v195 offset:3856
	v_add_f32_e32 v150, v147, v146
	v_add_f32_e32 v151, v148, v149
	v_add_f32_e32 v13, v151, v150
	v_cmp_eq_u32_e32 vcc, 14, v188
	s_nop 1
	v_cndmask_b32_e64 v202, 0, 1.0, vcc
	s_waitcnt lgkmcnt(0)
	v_pk_fma_f32 v[146:147], v[0:1], v[80:81], v[202:203] neg_lo:[1,0,0] neg_hi:[1,0,0]
	v_pk_fma_f32 v[148:149], v[2:3], v[82:83], v[200:201] neg_lo:[1,0,0] neg_hi:[1,0,0]
	ds_read_b128 v[80:83], v195 offset:4080
	v_pk_fma_f32 v[146:147], v[4:5], v[84:85], v[146:147] neg_lo:[1,0,0] neg_hi:[1,0,0]
	v_pk_fma_f32 v[148:149], v[6:7], v[86:87], v[148:149] neg_lo:[1,0,0] neg_hi:[1,0,0]
	ds_read_b128 v[84:87], v195 offset:4096
	v_pk_fma_f32 v[146:147], v[8:9], v[88:89], v[146:147] neg_lo:[1,0,0] neg_hi:[1,0,0]
	v_pk_fma_f32 v[148:149], v[10:11], v[90:91], v[148:149] neg_lo:[1,0,0] neg_hi:[1,0,0]
	ds_read_b128 v[88:91], v195 offset:4112
	v_pk_fma_f32 v[146:147], v[12:13], v[92:93], v[146:147] neg_lo:[1,0,0] neg_hi:[1,0,0]
	ds_read_b128 v[92:95], v195 offset:4128
	v_add_f32_e32 v150, v147, v146
	v_add_f32_e32 v151, v148, v149
	v_add_f32_e32 v14, v151, v150
	v_cmp_eq_u32_e32 vcc, 15, v188
	s_nop 1
	v_cndmask_b32_e64 v202, 0, 1.0, vcc
	s_waitcnt lgkmcnt(0)
	v_pk_fma_f32 v[146:147], v[0:1], v[80:81], v[202:203] neg_lo:[1,0,0] neg_hi:[1,0,0]
	v_pk_fma_f32 v[148:149], v[2:3], v[82:83], v[200:201] neg_lo:[1,0,0] neg_hi:[1,0,0]
	ds_read_b128 v[80:83], v195 offset:4352
	v_pk_fma_f32 v[146:147], v[4:5], v[84:85], v[146:147] neg_lo:[1,0,0] neg_hi:[1,0,0]
	v_pk_fma_f32 v[148:149], v[6:7], v[86:87], v[148:149] neg_lo:[1,0,0] neg_hi:[1,0,0]
	ds_read_b128 v[84:87], v195 offset:4368
	v_pk_fma_f32 v[146:147], v[8:9], v[88:89], v[146:147] neg_lo:[1,0,0] neg_hi:[1,0,0]
	v_pk_fma_f32 v[148:149], v[10:11], v[90:91], v[148:149] neg_lo:[1,0,0] neg_hi:[1,0,0]
	ds_read_b128 v[88:91], v195 offset:4384
	v_pk_fma_f32 v[146:147], v[12:13], v[92:93], v[146:147] neg_lo:[1,0,0] neg_hi:[1,0,0]
	v_fma_f32 v148, -v14, v94, v148
	ds_read_b128 v[92:95], v195 offset:4400
	v_add_f32_e32 v150, v147, v146
	v_add_f32_e32 v151, v148, v149
	v_add_f32_e32 v15, v151, v150
	v_cmp_eq_u32_e32 vcc, 16, v188
	s_nop 1
	v_cndmask_b32_e64 v202, 0, 1.0, vcc
	s_waitcnt lgkmcnt(0)
	v_pk_fma_f32 v[146:147], v[0:1], v[80:81], v[202:203] neg_lo:[1,0,0] neg_hi:[1,0,0]
	v_pk_fma_f32 v[148:149], v[2:3], v[82:83], v[200:201] neg_lo:[1,0,0] neg_hi:[1,0,0]
	ds_read_b128 v[80:83], v195 offset:4624
	v_pk_fma_f32 v[146:147], v[4:5], v[84:85], v[146:147] neg_lo:[1,0,0] neg_hi:[1,0,0]
	v_pk_fma_f32 v[148:149], v[6:7], v[86:87], v[148:149] neg_lo:[1,0,0] neg_hi:[1,0,0]
	ds_read_b128 v[84:87], v195 offset:4640
	v_pk_fma_f32 v[146:147], v[8:9], v[88:89], v[146:147] neg_lo:[1,0,0] neg_hi:[1,0,0]
	v_pk_fma_f32 v[148:149], v[10:11], v[90:91], v[148:149] neg_lo:[1,0,0] neg_hi:[1,0,0]
	ds_read_b128 v[88:91], v195 offset:4656
	v_pk_fma_f32 v[146:147], v[12:13], v[92:93], v[146:147] neg_lo:[1,0,0] neg_hi:[1,0,0]
	v_pk_fma_f32 v[148:149], v[14:15], v[94:95], v[148:149] neg_lo:[1,0,0] neg_hi:[1,0,0]
	ds_read_b128 v[92:95], v195 offset:4672
	ds_read_b128 v[96:99], v195 offset:4688
	v_add_f32_e32 v150, v147, v146
	v_add_f32_e32 v151, v148, v149
	v_add_f32_e32 v16, v151, v150
	v_cmp_eq_u32_e32 vcc, 17, v188
	s_nop 1
	v_cndmask_b32_e64 v202, 0, 1.0, vcc
	s_waitcnt lgkmcnt(1)
	v_pk_fma_f32 v[146:147], v[0:1], v[80:81], v[202:203] neg_lo:[1,0,0] neg_hi:[1,0,0]
	v_pk_fma_f32 v[148:149], v[2:3], v[82:83], v[200:201] neg_lo:[1,0,0] neg_hi:[1,0,0]
	ds_read_b128 v[80:83], v195 offset:4896
	v_pk_fma_f32 v[146:147], v[4:5], v[84:85], v[146:147] neg_lo:[1,0,0] neg_hi:[1,0,0]
	v_pk_fma_f32 v[148:149], v[6:7], v[86:87], v[148:149] neg_lo:[1,0,0] neg_hi:[1,0,0]
	ds_read_b128 v[84:87], v195 offset:4912
	v_pk_fma_f32 v[146:147], v[8:9], v[88:89], v[146:147] neg_lo:[1,0,0] neg_hi:[1,0,0]
	v_pk_fma_f32 v[148:149], v[10:11], v[90:91], v[148:149] neg_lo:[1,0,0] neg_hi:[1,0,0]
	ds_read_b128 v[88:91], v195 offset:4928
	v_pk_fma_f32 v[146:147], v[12:13], v[92:93], v[146:147] neg_lo:[1,0,0] neg_hi:[1,0,0]
	v_pk_fma_f32 v[148:149], v[14:15], v[94:95], v[148:149] neg_lo:[1,0,0] neg_hi:[1,0,0]
	ds_read_b128 v[92:95], v195 offset:4944
	s_waitcnt lgkmcnt(4)
	v_fma_f32 v146, -v16, v96, v146
	ds_read_b128 v[96:99], v195 offset:4960
	v_add_f32_e32 v150, v147, v146
	v_add_f32_e32 v151, v148, v149
	v_add_f32_e32 v17, v151, v150
	v_cmp_eq_u32_e32 vcc, 18, v188
	s_nop 1
	v_cndmask_b32_e64 v202, 0, 1.0, vcc
	s_waitcnt lgkmcnt(1)
	v_pk_fma_f32 v[146:147], v[0:1], v[80:81], v[202:203] neg_lo:[1,0,0] neg_hi:[1,0,0]
	v_pk_fma_f32 v[148:149], v[2:3], v[82:83], v[200:201] neg_lo:[1,0,0] neg_hi:[1,0,0]
	ds_read_b128 v[80:83], v195 offset:5168
	v_pk_fma_f32 v[146:147], v[4:5], v[84:85], v[146:147] neg_lo:[1,0,0] neg_hi:[1,0,0]
	v_pk_fma_f32 v[148:149], v[6:7], v[86:87], v[148:149] neg_lo:[1,0,0] neg_hi:[1,0,0]
	ds_read_b128 v[84:87], v195 offset:5184
	v_pk_fma_f32 v[146:147], v[8:9], v[88:89], v[146:147] neg_lo:[1,0,0] neg_hi:[1,0,0]
	v_pk_fma_f32 v[148:149], v[10:11], v[90:91], v[148:149] neg_lo:[1,0,0] neg_hi:[1,0,0]
	ds_read_b128 v[88:91], v195 offset:5200
	v_pk_fma_f32 v[146:147], v[12:13], v[92:93], v[146:147] neg_lo:[1,0,0] neg_hi:[1,0,0]
	v_pk_fma_f32 v[148:149], v[14:15], v[94:95], v[148:149] neg_lo:[1,0,0] neg_hi:[1,0,0]
	ds_read_b128 v[92:95], v195 offset:5216
	s_waitcnt lgkmcnt(4)
	v_pk_fma_f32 v[146:147], v[16:17], v[96:97], v[146:147] neg_lo:[1,0,0] neg_hi:[1,0,0]
	ds_read_b128 v[96:99], v195 offset:5232
	v_add_f32_e32 v150, v147, v146
	v_add_f32_e32 v151, v148, v149
	v_add_f32_e32 v18, v151, v150
	v_cmp_eq_u32_e32 vcc, 19, v188
	s_nop 1
	v_cndmask_b32_e64 v202, 0, 1.0, vcc
	s_waitcnt lgkmcnt(1)
	v_pk_fma_f32 v[146:147], v[0:1], v[80:81], v[202:203] neg_lo:[1,0,0] neg_hi:[1,0,0]
	v_pk_fma_f32 v[148:149], v[2:3], v[82:83], v[200:201] neg_lo:[1,0,0] neg_hi:[1,0,0]
	ds_read_b128 v[80:83], v195 offset:5440
	v_pk_fma_f32 v[146:147], v[4:5], v[84:85], v[146:147] neg_lo:[1,0,0] neg_hi:[1,0,0]
	v_pk_fma_f32 v[148:149], v[6:7], v[86:87], v[148:149] neg_lo:[1,0,0] neg_hi:[1,0,0]
	ds_read_b128 v[84:87], v195 offset:5456
	v_pk_fma_f32 v[146:147], v[8:9], v[88:89], v[146:147] neg_lo:[1,0,0] neg_hi:[1,0,0]
	v_pk_fma_f32 v[148:149], v[10:11], v[90:91], v[148:149] neg_lo:[1,0,0] neg_hi:[1,0,0]
	ds_read_b128 v[88:91], v195 offset:5472
	v_pk_fma_f32 v[146:147], v[12:13], v[92:93], v[146:147] neg_lo:[1,0,0] neg_hi:[1,0,0]
	v_pk_fma_f32 v[148:149], v[14:15], v[94:95], v[148:149] neg_lo:[1,0,0] neg_hi:[1,0,0]
	ds_read_b128 v[92:95], v195 offset:5488
	s_waitcnt lgkmcnt(4)
	v_pk_fma_f32 v[146:147], v[16:17], v[96:97], v[146:147] neg_lo:[1,0,0] neg_hi:[1,0,0]
	v_fma_f32 v148, -v18, v98, v148
	ds_read_b128 v[96:99], v195 offset:5504
	v_add_f32_e32 v150, v147, v146
	v_add_f32_e32 v151, v148, v149
	v_add_f32_e32 v19, v151, v150
	v_cmp_eq_u32_e32 vcc, 20, v188
	s_nop 1
	v_cndmask_b32_e64 v202, 0, 1.0, vcc
	s_waitcnt lgkmcnt(1)
	v_pk_fma_f32 v[146:147], v[0:1], v[80:81], v[202:203] neg_lo:[1,0,0] neg_hi:[1,0,0]
	v_pk_fma_f32 v[148:149], v[2:3], v[82:83], v[200:201] neg_lo:[1,0,0] neg_hi:[1,0,0]
	ds_read_b128 v[80:83], v195 offset:5712
	v_pk_fma_f32 v[146:147], v[4:5], v[84:85], v[146:147] neg_lo:[1,0,0] neg_hi:[1,0,0]
	v_pk_fma_f32 v[148:149], v[6:7], v[86:87], v[148:149] neg_lo:[1,0,0] neg_hi:[1,0,0]
	ds_read_b128 v[84:87], v195 offset:5728
	v_pk_fma_f32 v[146:147], v[8:9], v[88:89], v[146:147] neg_lo:[1,0,0] neg_hi:[1,0,0]
	v_pk_fma_f32 v[148:149], v[10:11], v[90:91], v[148:149] neg_lo:[1,0,0] neg_hi:[1,0,0]
	ds_read_b128 v[88:91], v195 offset:5744
	v_pk_fma_f32 v[146:147], v[12:13], v[92:93], v[146:147] neg_lo:[1,0,0] neg_hi:[1,0,0]
	v_pk_fma_f32 v[148:149], v[14:15], v[94:95], v[148:149] neg_lo:[1,0,0] neg_hi:[1,0,0]
	ds_read_b128 v[92:95], v195 offset:5760
	s_waitcnt lgkmcnt(4)
	v_pk_fma_f32 v[146:147], v[16:17], v[96:97], v[146:147] neg_lo:[1,0,0] neg_hi:[1,0,0]
	v_pk_fma_f32 v[148:149], v[18:19], v[98:99], v[148:149] neg_lo:[1,0,0] neg_hi:[1,0,0]
	ds_read_b128 v[96:99], v195 offset:5776
	ds_read_b128 v[100:103], v195 offset:5792
	v_add_f32_e32 v150, v147, v146
	v_add_f32_e32 v151, v148, v149
	v_add_f32_e32 v20, v151, v150
	v_cmp_eq_u32_e32 vcc, 21, v188
	s_nop 1
	v_cndmask_b32_e64 v202, 0, 1.0, vcc
	s_waitcnt lgkmcnt(2)
	v_pk_fma_f32 v[146:147], v[0:1], v[80:81], v[202:203] neg_lo:[1,0,0] neg_hi:[1,0,0]
	v_pk_fma_f32 v[148:149], v[2:3], v[82:83], v[200:201] neg_lo:[1,0,0] neg_hi:[1,0,0]
	ds_read_b128 v[80:83], v195 offset:5984
	v_pk_fma_f32 v[146:147], v[4:5], v[84:85], v[146:147] neg_lo:[1,0,0] neg_hi:[1,0,0]
	v_pk_fma_f32 v[148:149], v[6:7], v[86:87], v[148:149] neg_lo:[1,0,0] neg_hi:[1,0,0]
	ds_read_b128 v[84:87], v195 offset:6000
	v_pk_fma_f32 v[146:147], v[8:9], v[88:89], v[146:147] neg_lo:[1,0,0] neg_hi:[1,0,0]
	v_pk_fma_f32 v[148:149], v[10:11], v[90:91], v[148:149] neg_lo:[1,0,0] neg_hi:[1,0,0]
	ds_read_b128 v[88:91], v195 offset:6016
	v_pk_fma_f32 v[146:147], v[12:13], v[92:93], v[146:147] neg_lo:[1,0,0] neg_hi:[1,0,0]
	v_pk_fma_f32 v[148:149], v[14:15], v[94:95], v[148:149] neg_lo:[1,0,0] neg_hi:[1,0,0]
	ds_read_b128 v[92:95], v195 offset:6032
	s_waitcnt lgkmcnt(4)
	v_pk_fma_f32 v[146:147], v[16:17], v[96:97], v[146:147] neg_lo:[1,0,0] neg_hi:[1,0,0]
	v_pk_fma_f32 v[148:149], v[18:19], v[98:99], v[148:149] neg_lo:[1,0,0] neg_hi:[1,0,0]
	ds_read_b128 v[96:99], v195 offset:6048
	v_fma_f32 v146, -v20, v100, v146
	ds_read_b128 v[100:103], v195 offset:6064
	v_add_f32_e32 v150, v147, v146
	v_add_f32_e32 v151, v148, v149
	v_add_f32_e32 v21, v151, v150
	v_cmp_eq_u32_e32 vcc, 22, v188
	s_nop 1
	v_cndmask_b32_e64 v202, 0, 1.0, vcc
	s_waitcnt lgkmcnt(2)
	v_pk_fma_f32 v[146:147], v[0:1], v[80:81], v[202:203] neg_lo:[1,0,0] neg_hi:[1,0,0]
	v_pk_fma_f32 v[148:149], v[2:3], v[82:83], v[200:201] neg_lo:[1,0,0] neg_hi:[1,0,0]
	ds_read_b128 v[80:83], v195 offset:6256
	v_pk_fma_f32 v[146:147], v[4:5], v[84:85], v[146:147] neg_lo:[1,0,0] neg_hi:[1,0,0]
	v_pk_fma_f32 v[148:149], v[6:7], v[86:87], v[148:149] neg_lo:[1,0,0] neg_hi:[1,0,0]
	ds_read_b128 v[84:87], v195 offset:6272
	v_pk_fma_f32 v[146:147], v[8:9], v[88:89], v[146:147] neg_lo:[1,0,0] neg_hi:[1,0,0]
	v_pk_fma_f32 v[148:149], v[10:11], v[90:91], v[148:149] neg_lo:[1,0,0] neg_hi:[1,0,0]
	ds_read_b128 v[88:91], v195 offset:6288
	v_pk_fma_f32 v[146:147], v[12:13], v[92:93], v[146:147] neg_lo:[1,0,0] neg_hi:[1,0,0]
	v_pk_fma_f32 v[148:149], v[14:15], v[94:95], v[148:149] neg_lo:[1,0,0] neg_hi:[1,0,0]
	ds_read_b128 v[92:95], v195 offset:6304
	s_waitcnt lgkmcnt(4)
	v_pk_fma_f32 v[146:147], v[16:17], v[96:97], v[146:147] neg_lo:[1,0,0] neg_hi:[1,0,0]
	v_pk_fma_f32 v[148:149], v[18:19], v[98:99], v[148:149] neg_lo:[1,0,0] neg_hi:[1,0,0]
	ds_read_b128 v[96:99], v195 offset:6320
	v_pk_fma_f32 v[146:147], v[20:21], v[100:101], v[146:147] neg_lo:[1,0,0] neg_hi:[1,0,0]
	ds_read_b128 v[100:103], v195 offset:6336
	v_add_f32_e32 v150, v147, v146
	v_add_f32_e32 v151, v148, v149
	v_add_f32_e32 v22, v151, v150
	v_cmp_eq_u32_e32 vcc, 23, v188
	s_nop 1
	v_cndmask_b32_e64 v202, 0, 1.0, vcc
	s_waitcnt lgkmcnt(2)
	v_pk_fma_f32 v[146:147], v[0:1], v[80:81], v[202:203] neg_lo:[1,0,0] neg_hi:[1,0,0]
	v_pk_fma_f32 v[148:149], v[2:3], v[82:83], v[200:201] neg_lo:[1,0,0] neg_hi:[1,0,0]
	ds_read_b128 v[80:83], v195 offset:6528
	v_pk_fma_f32 v[146:147], v[4:5], v[84:85], v[146:147] neg_lo:[1,0,0] neg_hi:[1,0,0]
	v_pk_fma_f32 v[148:149], v[6:7], v[86:87], v[148:149] neg_lo:[1,0,0] neg_hi:[1,0,0]
	ds_read_b128 v[84:87], v195 offset:6544
	v_pk_fma_f32 v[146:147], v[8:9], v[88:89], v[146:147] neg_lo:[1,0,0] neg_hi:[1,0,0]
	v_pk_fma_f32 v[148:149], v[10:11], v[90:91], v[148:149] neg_lo:[1,0,0] neg_hi:[1,0,0]
	ds_read_b128 v[88:91], v195 offset:6560
	v_pk_fma_f32 v[146:147], v[12:13], v[92:93], v[146:147] neg_lo:[1,0,0] neg_hi:[1,0,0]
	v_pk_fma_f32 v[148:149], v[14:15], v[94:95], v[148:149] neg_lo:[1,0,0] neg_hi:[1,0,0]
	ds_read_b128 v[92:95], v195 offset:6576
	s_waitcnt lgkmcnt(4)
	v_pk_fma_f32 v[146:147], v[16:17], v[96:97], v[146:147] neg_lo:[1,0,0] neg_hi:[1,0,0]
	v_pk_fma_f32 v[148:149], v[18:19], v[98:99], v[148:149] neg_lo:[1,0,0] neg_hi:[1,0,0]
	ds_read_b128 v[96:99], v195 offset:6592
	v_pk_fma_f32 v[146:147], v[20:21], v[100:101], v[146:147] neg_lo:[1,0,0] neg_hi:[1,0,0]
	v_fma_f32 v148, -v22, v102, v148
	ds_read_b128 v[100:103], v195 offset:6608
	v_add_f32_e32 v150, v147, v146
	v_add_f32_e32 v151, v148, v149
	v_add_f32_e32 v23, v151, v150
	v_cmp_eq_u32_e32 vcc, 24, v188
	s_nop 1
	v_cndmask_b32_e64 v202, 0, 1.0, vcc
	s_waitcnt lgkmcnt(2)
	v_pk_fma_f32 v[146:147], v[0:1], v[80:81], v[202:203] neg_lo:[1,0,0] neg_hi:[1,0,0]
	v_pk_fma_f32 v[148:149], v[2:3], v[82:83], v[200:201] neg_lo:[1,0,0] neg_hi:[1,0,0]
	ds_read_b128 v[80:83], v195 offset:6800
	v_pk_fma_f32 v[146:147], v[4:5], v[84:85], v[146:147] neg_lo:[1,0,0] neg_hi:[1,0,0]
	v_pk_fma_f32 v[148:149], v[6:7], v[86:87], v[148:149] neg_lo:[1,0,0] neg_hi:[1,0,0]
	ds_read_b128 v[84:87], v195 offset:6816
	v_pk_fma_f32 v[146:147], v[8:9], v[88:89], v[146:147] neg_lo:[1,0,0] neg_hi:[1,0,0]
	v_pk_fma_f32 v[148:149], v[10:11], v[90:91], v[148:149] neg_lo:[1,0,0] neg_hi:[1,0,0]
	ds_read_b128 v[88:91], v195 offset:6832
	v_pk_fma_f32 v[146:147], v[12:13], v[92:93], v[146:147] neg_lo:[1,0,0] neg_hi:[1,0,0]
	v_pk_fma_f32 v[148:149], v[14:15], v[94:95], v[148:149] neg_lo:[1,0,0] neg_hi:[1,0,0]
	ds_read_b128 v[92:95], v195 offset:6848
	s_waitcnt lgkmcnt(4)
	v_pk_fma_f32 v[146:147], v[16:17], v[96:97], v[146:147] neg_lo:[1,0,0] neg_hi:[1,0,0]
	v_pk_fma_f32 v[148:149], v[18:19], v[98:99], v[148:149] neg_lo:[1,0,0] neg_hi:[1,0,0]
	ds_read_b128 v[96:99], v195 offset:6864
	v_pk_fma_f32 v[146:147], v[20:21], v[100:101], v[146:147] neg_lo:[1,0,0] neg_hi:[1,0,0]
	v_pk_fma_f32 v[148:149], v[22:23], v[102:103], v[148:149] neg_lo:[1,0,0] neg_hi:[1,0,0]
	ds_read_b128 v[100:103], v195 offset:6880
	ds_read_b128 v[104:107], v195 offset:6896
	v_add_f32_e32 v150, v147, v146
	v_add_f32_e32 v151, v148, v149
	v_add_f32_e32 v24, v151, v150
	v_cmp_eq_u32_e32 vcc, 25, v188
	s_nop 1
	v_cndmask_b32_e64 v202, 0, 1.0, vcc
	s_waitcnt lgkmcnt(3)
	v_pk_fma_f32 v[146:147], v[0:1], v[80:81], v[202:203] neg_lo:[1,0,0] neg_hi:[1,0,0]
	v_pk_fma_f32 v[148:149], v[2:3], v[82:83], v[200:201] neg_lo:[1,0,0] neg_hi:[1,0,0]
	ds_read_b128 v[80:83], v195 offset:7072
	v_pk_fma_f32 v[146:147], v[4:5], v[84:85], v[146:147] neg_lo:[1,0,0] neg_hi:[1,0,0]
	v_pk_fma_f32 v[148:149], v[6:7], v[86:87], v[148:149] neg_lo:[1,0,0] neg_hi:[1,0,0]
	ds_read_b128 v[84:87], v195 offset:7088
	v_pk_fma_f32 v[146:147], v[8:9], v[88:89], v[146:147] neg_lo:[1,0,0] neg_hi:[1,0,0]
	v_pk_fma_f32 v[148:149], v[10:11], v[90:91], v[148:149] neg_lo:[1,0,0] neg_hi:[1,0,0]
	ds_read_b128 v[88:91], v195 offset:7104
	v_pk_fma_f32 v[146:147], v[12:13], v[92:93], v[146:147] neg_lo:[1,0,0] neg_hi:[1,0,0]
	v_pk_fma_f32 v[148:149], v[14:15], v[94:95], v[148:149] neg_lo:[1,0,0] neg_hi:[1,0,0]
	ds_read_b128 v[92:95], v195 offset:7120
	s_waitcnt lgkmcnt(4)
	v_pk_fma_f32 v[146:147], v[16:17], v[96:97], v[146:147] neg_lo:[1,0,0] neg_hi:[1,0,0]
	v_pk_fma_f32 v[148:149], v[18:19], v[98:99], v[148:149] neg_lo:[1,0,0] neg_hi:[1,0,0]
	ds_read_b128 v[96:99], v195 offset:7136
	v_pk_fma_f32 v[146:147], v[20:21], v[100:101], v[146:147] neg_lo:[1,0,0] neg_hi:[1,0,0]
	v_pk_fma_f32 v[148:149], v[22:23], v[102:103], v[148:149] neg_lo:[1,0,0] neg_hi:[1,0,0]
	ds_read_b128 v[100:103], v195 offset:7152
	v_fma_f32 v146, -v24, v104, v146
	ds_read_b128 v[104:107], v195 offset:7168
	v_add_f32_e32 v150, v147, v146
	v_add_f32_e32 v151, v148, v149
	v_add_f32_e32 v25, v151, v150
	v_cmp_eq_u32_e32 vcc, 26, v188
	s_nop 1
	v_cndmask_b32_e64 v202, 0, 1.0, vcc
	s_waitcnt lgkmcnt(3)
	v_pk_fma_f32 v[146:147], v[0:1], v[80:81], v[202:203] neg_lo:[1,0,0] neg_hi:[1,0,0]
	v_pk_fma_f32 v[148:149], v[2:3], v[82:83], v[200:201] neg_lo:[1,0,0] neg_hi:[1,0,0]
	ds_read_b128 v[80:83], v195 offset:7344
	v_pk_fma_f32 v[146:147], v[4:5], v[84:85], v[146:147] neg_lo:[1,0,0] neg_hi:[1,0,0]
	v_pk_fma_f32 v[148:149], v[6:7], v[86:87], v[148:149] neg_lo:[1,0,0] neg_hi:[1,0,0]
	ds_read_b128 v[84:87], v195 offset:7360
	v_pk_fma_f32 v[146:147], v[8:9], v[88:89], v[146:147] neg_lo:[1,0,0] neg_hi:[1,0,0]
	v_pk_fma_f32 v[148:149], v[10:11], v[90:91], v[148:149] neg_lo:[1,0,0] neg_hi:[1,0,0]
	ds_read_b128 v[88:91], v195 offset:7376
	v_pk_fma_f32 v[146:147], v[12:13], v[92:93], v[146:147] neg_lo:[1,0,0] neg_hi:[1,0,0]
	v_pk_fma_f32 v[148:149], v[14:15], v[94:95], v[148:149] neg_lo:[1,0,0] neg_hi:[1,0,0]
	ds_read_b128 v[92:95], v195 offset:7392
	s_waitcnt lgkmcnt(4)
	v_pk_fma_f32 v[146:147], v[16:17], v[96:97], v[146:147] neg_lo:[1,0,0] neg_hi:[1,0,0]
	v_pk_fma_f32 v[148:149], v[18:19], v[98:99], v[148:149] neg_lo:[1,0,0] neg_hi:[1,0,0]
	ds_read_b128 v[96:99], v195 offset:7408
	v_pk_fma_f32 v[146:147], v[20:21], v[100:101], v[146:147] neg_lo:[1,0,0] neg_hi:[1,0,0]
	v_pk_fma_f32 v[148:149], v[22:23], v[102:103], v[148:149] neg_lo:[1,0,0] neg_hi:[1,0,0]
	ds_read_b128 v[100:103], v195 offset:7424
	v_pk_fma_f32 v[146:147], v[24:25], v[104:105], v[146:147] neg_lo:[1,0,0] neg_hi:[1,0,0]
	ds_read_b128 v[104:107], v195 offset:7440
	v_add_f32_e32 v150, v147, v146
	v_add_f32_e32 v151, v148, v149
	v_add_f32_e32 v26, v151, v150
	v_cmp_eq_u32_e32 vcc, 27, v188
	s_nop 1
	v_cndmask_b32_e64 v202, 0, 1.0, vcc
	s_waitcnt lgkmcnt(3)
	v_pk_fma_f32 v[146:147], v[0:1], v[80:81], v[202:203] neg_lo:[1,0,0] neg_hi:[1,0,0]
	v_pk_fma_f32 v[148:149], v[2:3], v[82:83], v[200:201] neg_lo:[1,0,0] neg_hi:[1,0,0]
	ds_read_b128 v[80:83], v195 offset:7616
	v_pk_fma_f32 v[146:147], v[4:5], v[84:85], v[146:147] neg_lo:[1,0,0] neg_hi:[1,0,0]
	v_pk_fma_f32 v[148:149], v[6:7], v[86:87], v[148:149] neg_lo:[1,0,0] neg_hi:[1,0,0]
	ds_read_b128 v[84:87], v195 offset:7632
	v_pk_fma_f32 v[146:147], v[8:9], v[88:89], v[146:147] neg_lo:[1,0,0] neg_hi:[1,0,0]
	v_pk_fma_f32 v[148:149], v[10:11], v[90:91], v[148:149] neg_lo:[1,0,0] neg_hi:[1,0,0]
	ds_read_b128 v[88:91], v195 offset:7648
	v_pk_fma_f32 v[146:147], v[12:13], v[92:93], v[146:147] neg_lo:[1,0,0] neg_hi:[1,0,0]
	v_pk_fma_f32 v[148:149], v[14:15], v[94:95], v[148:149] neg_lo:[1,0,0] neg_hi:[1,0,0]
	ds_read_b128 v[92:95], v195 offset:7664
	s_waitcnt lgkmcnt(4)
	v_pk_fma_f32 v[146:147], v[16:17], v[96:97], v[146:147] neg_lo:[1,0,0] neg_hi:[1,0,0]
	v_pk_fma_f32 v[148:149], v[18:19], v[98:99], v[148:149] neg_lo:[1,0,0] neg_hi:[1,0,0]
	ds_read_b128 v[96:99], v195 offset:7680
	v_pk_fma_f32 v[146:147], v[20:21], v[100:101], v[146:147] neg_lo:[1,0,0] neg_hi:[1,0,0]
	v_pk_fma_f32 v[148:149], v[22:23], v[102:103], v[148:149] neg_lo:[1,0,0] neg_hi:[1,0,0]
	ds_read_b128 v[100:103], v195 offset:7696
	v_pk_fma_f32 v[146:147], v[24:25], v[104:105], v[146:147] neg_lo:[1,0,0] neg_hi:[1,0,0]
	v_fma_f32 v148, -v26, v106, v148
	ds_read_b128 v[104:107], v195 offset:7712
	v_add_f32_e32 v150, v147, v146
	v_add_f32_e32 v151, v148, v149
	v_add_f32_e32 v27, v151, v150
	v_cmp_eq_u32_e32 vcc, 28, v188
	s_nop 1
	v_cndmask_b32_e64 v202, 0, 1.0, vcc
	s_waitcnt lgkmcnt(3)
	v_pk_fma_f32 v[146:147], v[0:1], v[80:81], v[202:203] neg_lo:[1,0,0] neg_hi:[1,0,0]
	v_pk_fma_f32 v[148:149], v[2:3], v[82:83], v[200:201] neg_lo:[1,0,0] neg_hi:[1,0,0]
	ds_read_b128 v[80:83], v195 offset:7888
	v_pk_fma_f32 v[146:147], v[4:5], v[84:85], v[146:147] neg_lo:[1,0,0] neg_hi:[1,0,0]
	v_pk_fma_f32 v[148:149], v[6:7], v[86:87], v[148:149] neg_lo:[1,0,0] neg_hi:[1,0,0]
	ds_read_b128 v[84:87], v195 offset:7904
	v_pk_fma_f32 v[146:147], v[8:9], v[88:89], v[146:147] neg_lo:[1,0,0] neg_hi:[1,0,0]
	v_pk_fma_f32 v[148:149], v[10:11], v[90:91], v[148:149] neg_lo:[1,0,0] neg_hi:[1,0,0]
	ds_read_b128 v[88:91], v195 offset:7920
	v_pk_fma_f32 v[146:147], v[12:13], v[92:93], v[146:147] neg_lo:[1,0,0] neg_hi:[1,0,0]
	v_pk_fma_f32 v[148:149], v[14:15], v[94:95], v[148:149] neg_lo:[1,0,0] neg_hi:[1,0,0]
	ds_read_b128 v[92:95], v195 offset:7936
	s_waitcnt lgkmcnt(4)
	v_pk_fma_f32 v[146:147], v[16:17], v[96:97], v[146:147] neg_lo:[1,0,0] neg_hi:[1,0,0]
	v_pk_fma_f32 v[148:149], v[18:19], v[98:99], v[148:149] neg_lo:[1,0,0] neg_hi:[1,0,0]
	ds_read_b128 v[96:99], v195 offset:7952
	v_pk_fma_f32 v[146:147], v[20:21], v[100:101], v[146:147] neg_lo:[1,0,0] neg_hi:[1,0,0]
	v_pk_fma_f32 v[148:149], v[22:23], v[102:103], v[148:149] neg_lo:[1,0,0] neg_hi:[1,0,0]
	ds_read_b128 v[100:103], v195 offset:7968
	v_pk_fma_f32 v[146:147], v[24:25], v[104:105], v[146:147] neg_lo:[1,0,0] neg_hi:[1,0,0]
	v_pk_fma_f32 v[148:149], v[26:27], v[106:107], v[148:149] neg_lo:[1,0,0] neg_hi:[1,0,0]
	ds_read_b128 v[104:107], v195 offset:7984
	ds_read_b128 v[108:111], v195 offset:8000
	v_add_f32_e32 v150, v147, v146
	v_add_f32_e32 v151, v148, v149
	v_add_f32_e32 v28, v151, v150
	v_cmp_eq_u32_e32 vcc, 29, v188
	s_nop 1
	v_cndmask_b32_e64 v202, 0, 1.0, vcc
	s_waitcnt lgkmcnt(4)
	v_pk_fma_f32 v[146:147], v[0:1], v[80:81], v[202:203] neg_lo:[1,0,0] neg_hi:[1,0,0]
	v_pk_fma_f32 v[148:149], v[2:3], v[82:83], v[200:201] neg_lo:[1,0,0] neg_hi:[1,0,0]
	ds_read_b128 v[80:83], v195 offset:8160
	v_pk_fma_f32 v[146:147], v[4:5], v[84:85], v[146:147] neg_lo:[1,0,0] neg_hi:[1,0,0]
	v_pk_fma_f32 v[148:149], v[6:7], v[86:87], v[148:149] neg_lo:[1,0,0] neg_hi:[1,0,0]
	ds_read_b128 v[84:87], v195 offset:8176
	v_pk_fma_f32 v[146:147], v[8:9], v[88:89], v[146:147] neg_lo:[1,0,0] neg_hi:[1,0,0]
	v_pk_fma_f32 v[148:149], v[10:11], v[90:91], v[148:149] neg_lo:[1,0,0] neg_hi:[1,0,0]
	ds_read_b128 v[88:91], v195 offset:8192
	v_pk_fma_f32 v[146:147], v[12:13], v[92:93], v[146:147] neg_lo:[1,0,0] neg_hi:[1,0,0]
	v_pk_fma_f32 v[148:149], v[14:15], v[94:95], v[148:149] neg_lo:[1,0,0] neg_hi:[1,0,0]
	ds_read_b128 v[92:95], v195 offset:8208
	s_waitcnt lgkmcnt(4)
	v_pk_fma_f32 v[146:147], v[16:17], v[96:97], v[146:147] neg_lo:[1,0,0] neg_hi:[1,0,0]
	v_pk_fma_f32 v[148:149], v[18:19], v[98:99], v[148:149] neg_lo:[1,0,0] neg_hi:[1,0,0]
	ds_read_b128 v[96:99], v195 offset:8224
	v_pk_fma_f32 v[146:147], v[20:21], v[100:101], v[146:147] neg_lo:[1,0,0] neg_hi:[1,0,0]
	v_pk_fma_f32 v[148:149], v[22:23], v[102:103], v[148:149] neg_lo:[1,0,0] neg_hi:[1,0,0]
	ds_read_b128 v[100:103], v195 offset:8240
	v_pk_fma_f32 v[146:147], v[24:25], v[104:105], v[146:147] neg_lo:[1,0,0] neg_hi:[1,0,0]
	v_pk_fma_f32 v[148:149], v[26:27], v[106:107], v[148:149] neg_lo:[1,0,0] neg_hi:[1,0,0]
	ds_read_b128 v[104:107], v195 offset:8256
	v_fma_f32 v146, -v28, v108, v146
	ds_read_b128 v[108:111], v195 offset:8272
	v_add_f32_e32 v150, v147, v146
	v_add_f32_e32 v151, v148, v149
	v_add_f32_e32 v29, v151, v150
	v_cmp_eq_u32_e32 vcc, 30, v188
	s_nop 1
	v_cndmask_b32_e64 v202, 0, 1.0, vcc
	s_waitcnt lgkmcnt(4)
	v_pk_fma_f32 v[146:147], v[0:1], v[80:81], v[202:203] neg_lo:[1,0,0] neg_hi:[1,0,0]
	v_pk_fma_f32 v[148:149], v[2:3], v[82:83], v[200:201] neg_lo:[1,0,0] neg_hi:[1,0,0]
	ds_read_b128 v[80:83], v195 offset:8432
	v_pk_fma_f32 v[146:147], v[4:5], v[84:85], v[146:147] neg_lo:[1,0,0] neg_hi:[1,0,0]
	v_pk_fma_f32 v[148:149], v[6:7], v[86:87], v[148:149] neg_lo:[1,0,0] neg_hi:[1,0,0]
	ds_read_b128 v[84:87], v195 offset:8448
	v_pk_fma_f32 v[146:147], v[8:9], v[88:89], v[146:147] neg_lo:[1,0,0] neg_hi:[1,0,0]
	v_pk_fma_f32 v[148:149], v[10:11], v[90:91], v[148:149] neg_lo:[1,0,0] neg_hi:[1,0,0]
	ds_read_b128 v[88:91], v195 offset:8464
	v_pk_fma_f32 v[146:147], v[12:13], v[92:93], v[146:147] neg_lo:[1,0,0] neg_hi:[1,0,0]
	v_pk_fma_f32 v[148:149], v[14:15], v[94:95], v[148:149] neg_lo:[1,0,0] neg_hi:[1,0,0]
	ds_read_b128 v[92:95], v195 offset:8480
	s_waitcnt lgkmcnt(4)
	v_pk_fma_f32 v[146:147], v[16:17], v[96:97], v[146:147] neg_lo:[1,0,0] neg_hi:[1,0,0]
	v_pk_fma_f32 v[148:149], v[18:19], v[98:99], v[148:149] neg_lo:[1,0,0] neg_hi:[1,0,0]
	ds_read_b128 v[96:99], v195 offset:8496
	v_pk_fma_f32 v[146:147], v[20:21], v[100:101], v[146:147] neg_lo:[1,0,0] neg_hi:[1,0,0]
	v_pk_fma_f32 v[148:149], v[22:23], v[102:103], v[148:149] neg_lo:[1,0,0] neg_hi:[1,0,0]
	ds_read_b128 v[100:103], v195 offset:8512
	v_pk_fma_f32 v[146:147], v[24:25], v[104:105], v[146:147] neg_lo:[1,0,0] neg_hi:[1,0,0]
	v_pk_fma_f32 v[148:149], v[26:27], v[106:107], v[148:149] neg_lo:[1,0,0] neg_hi:[1,0,0]
	ds_read_b128 v[104:107], v195 offset:8528
	v_pk_fma_f32 v[146:147], v[28:29], v[108:109], v[146:147] neg_lo:[1,0,0] neg_hi:[1,0,0]
	ds_read_b128 v[108:111], v195 offset:8544
	v_add_f32_e32 v150, v147, v146
	v_add_f32_e32 v151, v148, v149
	v_add_f32_e32 v30, v151, v150
	v_cmp_eq_u32_e32 vcc, 31, v188
	s_nop 1
	v_cndmask_b32_e64 v202, 0, 1.0, vcc
	s_waitcnt lgkmcnt(4)
	v_pk_fma_f32 v[146:147], v[0:1], v[80:81], v[202:203] neg_lo:[1,0,0] neg_hi:[1,0,0]
	v_pk_fma_f32 v[148:149], v[2:3], v[82:83], v[200:201] neg_lo:[1,0,0] neg_hi:[1,0,0]
	v_pk_fma_f32 v[146:147], v[4:5], v[84:85], v[146:147] neg_lo:[1,0,0] neg_hi:[1,0,0]
	v_pk_fma_f32 v[148:149], v[6:7], v[86:87], v[148:149] neg_lo:[1,0,0] neg_hi:[1,0,0]
	v_pk_fma_f32 v[146:147], v[8:9], v[88:89], v[146:147] neg_lo:[1,0,0] neg_hi:[1,0,0]
	v_pk_fma_f32 v[148:149], v[10:11], v[90:91], v[148:149] neg_lo:[1,0,0] neg_hi:[1,0,0]
	v_pk_fma_f32 v[146:147], v[12:13], v[92:93], v[146:147] neg_lo:[1,0,0] neg_hi:[1,0,0]
	v_pk_fma_f32 v[148:149], v[14:15], v[94:95], v[148:149] neg_lo:[1,0,0] neg_hi:[1,0,0]
	s_waitcnt lgkmcnt(0)
	v_pk_fma_f32 v[146:147], v[16:17], v[96:97], v[146:147] neg_lo:[1,0,0] neg_hi:[1,0,0]
	v_pk_fma_f32 v[148:149], v[18:19], v[98:99], v[148:149] neg_lo:[1,0,0] neg_hi:[1,0,0]
	v_pk_fma_f32 v[146:147], v[20:21], v[100:101], v[146:147] neg_lo:[1,0,0] neg_hi:[1,0,0]
	v_pk_fma_f32 v[148:149], v[22:23], v[102:103], v[148:149] neg_lo:[1,0,0] neg_hi:[1,0,0]
	v_pk_fma_f32 v[146:147], v[24:25], v[104:105], v[146:147] neg_lo:[1,0,0] neg_hi:[1,0,0]
	v_pk_fma_f32 v[148:149], v[26:27], v[106:107], v[148:149] neg_lo:[1,0,0] neg_hi:[1,0,0]
	v_pk_fma_f32 v[146:147], v[28:29], v[108:109], v[146:147] neg_lo:[1,0,0] neg_hi:[1,0,0]
	v_fma_f32 v148, -v30, v110, v148
	v_add_f32_e32 v150, v147, v146
	v_add_f32_e32 v151, v148, v149
	v_add_f32_e32 v31, v151, v150
	ds_write_b32 v198, v0
	ds_write_b32 v198, v1 offset:128
	ds_write_b32 v198, v2 offset:256
	ds_write_b32 v198, v3 offset:384
	ds_write_b32 v198, v4 offset:512
	ds_write_b32 v198, v5 offset:640
	ds_write_b32 v198, v6 offset:768
	ds_write_b32 v198, v7 offset:896
	ds_write_b32 v198, v8 offset:1024
	ds_write_b32 v198, v9 offset:1152
	ds_write_b32 v198, v10 offset:1280
	ds_write_b32 v198, v11 offset:1408
	ds_write_b32 v198, v12 offset:1536
	ds_write_b32 v198, v13 offset:1664
	ds_write_b32 v198, v14 offset:1792
	s_waitcnt lgkmcnt(14)
	ds_write_b32 v198, v15 offset:1920
	s_waitcnt lgkmcnt(14)
	ds_write_b32 v198, v16 offset:2048
	s_waitcnt lgkmcnt(14)
	ds_write_b32 v198, v17 offset:2176
	s_waitcnt lgkmcnt(14)
	ds_write_b32 v198, v18 offset:2304
	s_waitcnt lgkmcnt(14)
	ds_write_b32 v198, v19 offset:2432
	s_waitcnt lgkmcnt(14)
	ds_write_b32 v198, v20 offset:2560
	s_waitcnt lgkmcnt(14)
	ds_write_b32 v198, v21 offset:2688
	s_waitcnt lgkmcnt(14)
	ds_write_b32 v198, v22 offset:2816
	s_waitcnt lgkmcnt(14)
	ds_write_b32 v198, v23 offset:2944
	s_waitcnt lgkmcnt(14)
	ds_write_b32 v198, v24 offset:3072
	s_waitcnt lgkmcnt(14)
	ds_write_b32 v198, v25 offset:3200
	s_waitcnt lgkmcnt(14)
	ds_write_b32 v198, v26 offset:3328
	s_waitcnt lgkmcnt(14)
	ds_write_b32 v198, v27 offset:3456
	s_waitcnt lgkmcnt(14)
	ds_write_b32 v198, v28 offset:3584
	s_waitcnt lgkmcnt(14)
	ds_write_b32 v198, v29 offset:3712
	s_waitcnt lgkmcnt(14)
	ds_write_b32 v198, v30 offset:3840
	s_waitcnt lgkmcnt(14)
	ds_write_b32 v198, v31 offset:3968
	v_mov_b32_e32 v32, v0
	v_mov_b32_e32 v204, v0
	v_mov_b32_e32 v33, v1
	v_mov_b32_e32 v205, v1
	s_nop 1
	v_permlane32_swap_b32_e32 v32, v204
	v_permlane32_swap_b32_e32 v33, v205
	v_mov_b32_e32 v34, v2
	v_mov_b32_e32 v204, v2
	v_mov_b32_e32 v35, v3
	v_mov_b32_e32 v205, v3
	s_nop 1
	v_permlane32_swap_b32_e32 v34, v204
	v_permlane32_swap_b32_e32 v35, v205
	v_mov_b32_e32 v36, v4
	v_mov_b32_e32 v204, v4
	v_mov_b32_e32 v37, v5
	v_mov_b32_e32 v205, v5
	s_nop 1
	v_permlane32_swap_b32_e32 v36, v204
	v_permlane32_swap_b32_e32 v37, v205
	v_mov_b32_e32 v38, v6
	v_mov_b32_e32 v204, v6
	v_mov_b32_e32 v39, v7
	v_mov_b32_e32 v205, v7
	s_nop 1
	v_permlane32_swap_b32_e32 v38, v204
	v_permlane32_swap_b32_e32 v39, v205
	v_mov_b32_e32 v40, v8
	v_mov_b32_e32 v204, v8
	v_mov_b32_e32 v41, v9
	v_mov_b32_e32 v205, v9
	s_nop 1
	v_permlane32_swap_b32_e32 v40, v204
	v_permlane32_swap_b32_e32 v41, v205
	v_mov_b32_e32 v42, v10
	v_mov_b32_e32 v204, v10
	v_mov_b32_e32 v43, v11
	v_mov_b32_e32 v205, v11
	s_nop 1
	v_permlane32_swap_b32_e32 v42, v204
	v_permlane32_swap_b32_e32 v43, v205
	v_mov_b32_e32 v44, v12
	v_mov_b32_e32 v204, v12
	v_mov_b32_e32 v45, v13
	v_mov_b32_e32 v205, v13
	s_nop 1
	v_permlane32_swap_b32_e32 v44, v204
	v_permlane32_swap_b32_e32 v45, v205
	v_mov_b32_e32 v46, v14
	v_mov_b32_e32 v204, v14
	v_mov_b32_e32 v47, v15
	v_mov_b32_e32 v205, v15
	s_nop 1
	v_permlane32_swap_b32_e32 v46, v204
	v_permlane32_swap_b32_e32 v47, v205
	v_mov_b32_e32 v48, v16
	v_mov_b32_e32 v204, v16
	v_mov_b32_e32 v49, v17
	v_mov_b32_e32 v205, v17
	s_nop 1
	v_permlane32_swap_b32_e32 v48, v204
	v_permlane32_swap_b32_e32 v49, v205
	v_mov_b32_e32 v50, v18
	v_mov_b32_e32 v204, v18
	v_mov_b32_e32 v51, v19
	v_mov_b32_e32 v205, v19
	s_nop 1
	v_permlane32_swap_b32_e32 v50, v204
	v_permlane32_swap_b32_e32 v51, v205
	v_mov_b32_e32 v52, v20
	v_mov_b32_e32 v204, v20
	v_mov_b32_e32 v53, v21
	v_mov_b32_e32 v205, v21
	s_nop 1
	v_permlane32_swap_b32_e32 v52, v204
	v_permlane32_swap_b32_e32 v53, v205
	v_mov_b32_e32 v54, v22
	v_mov_b32_e32 v204, v22
	v_mov_b32_e32 v55, v23
	v_mov_b32_e32 v205, v23
	s_nop 1
	v_permlane32_swap_b32_e32 v54, v204
	v_permlane32_swap_b32_e32 v55, v205
	v_mov_b32_e32 v56, v24
	v_mov_b32_e32 v204, v24
	v_mov_b32_e32 v57, v25
	v_mov_b32_e32 v205, v25
	s_nop 1
	v_permlane32_swap_b32_e32 v56, v204
	v_permlane32_swap_b32_e32 v57, v205
	v_mov_b32_e32 v58, v26
	v_mov_b32_e32 v204, v26
	v_mov_b32_e32 v59, v27
	v_mov_b32_e32 v205, v27
	s_nop 1
	v_permlane32_swap_b32_e32 v58, v204
	v_permlane32_swap_b32_e32 v59, v205
	v_mov_b32_e32 v60, v28
	v_mov_b32_e32 v204, v28
	v_mov_b32_e32 v61, v29
	v_mov_b32_e32 v205, v29
	s_nop 1
	v_permlane32_swap_b32_e32 v60, v204
	v_permlane32_swap_b32_e32 v61, v205
	v_mov_b32_e32 v62, v30
	v_mov_b32_e32 v204, v30
	v_mov_b32_e32 v63, v31
	v_mov_b32_e32 v205, v31
	s_nop 1
	v_permlane32_swap_b32_e32 v62, v204
	v_permlane32_swap_b32_e32 v63, v205
	s_waitcnt lgkmcnt(14)
	ds_read_b128 v[80:83], v196 offset:0
	s_waitcnt lgkmcnt(14)
	ds_read_b128 v[84:87], v196 offset:16
	s_waitcnt lgkmcnt(14)
	ds_read_b128 v[88:91], v196 offset:32
	s_waitcnt lgkmcnt(14)
	ds_read_b128 v[92:95], v196 offset:48
	s_waitcnt lgkmcnt(14)
	ds_read_b128 v[96:99], v196 offset:64
	s_waitcnt lgkmcnt(14)
	ds_read_b128 v[100:103], v196 offset:80
	s_waitcnt lgkmcnt(14)
	ds_read_b128 v[104:107], v196 offset:96
	s_waitcnt lgkmcnt(14)
	ds_read_b128 v[108:111], v196 offset:112
	s_waitcnt lgkmcnt(14)
	ds_read_b128 v[112:115], v196 offset:272
	s_waitcnt lgkmcnt(14)
	ds_read_b128 v[116:119], v196 offset:288
	s_waitcnt lgkmcnt(14)
	ds_read_b128 v[120:123], v196 offset:304
	s_waitcnt lgkmcnt(14)
	ds_read_b128 v[124:127], v196 offset:320
	s_waitcnt lgkmcnt(14)
	ds_read_b128 v[130:133], v196 offset:336
	s_waitcnt lgkmcnt(14)
	ds_read_b128 v[134:137], v196 offset:352
	s_waitcnt lgkmcnt(14)
	ds_read_b128 v[138:141], v196 offset:368
	s_waitcnt lgkmcnt(14)
	ds_read_b128 v[142:145], v196 offset:384
	s_waitcnt lgkmcnt(12)
	v_pk_fma_f32 v[146:147], v[80:81], v[32:33], v[200:201]
	v_pk_fma_f32 v[148:149], v[82:83], v[34:35], v[200:201]
	v_pk_fma_f32 v[146:147], v[84:85], v[36:37], v[146:147]
	v_pk_fma_f32 v[148:149], v[86:87], v[38:39], v[148:149]
	v_pk_fma_f32 v[146:147], v[88:89], v[40:41], v[146:147]
	v_pk_fma_f32 v[148:149], v[90:91], v[42:43], v[148:149]
	v_pk_fma_f32 v[146:147], v[92:93], v[44:45], v[146:147]
	v_pk_fma_f32 v[148:149], v[94:95], v[46:47], v[148:149]
	s_waitcnt lgkmcnt(8)
	v_pk_fma_f32 v[146:147], v[96:97], v[48:49], v[146:147]
	v_pk_fma_f32 v[148:149], v[98:99], v[50:51], v[148:149]
	v_pk_fma_f32 v[146:147], v[100:101], v[52:53], v[146:147]
	v_pk_fma_f32 v[148:149], v[102:103], v[54:55], v[148:149]
	v_pk_fma_f32 v[146:147], v[104:105], v[56:57], v[146:147]
	v_pk_fma_f32 v[148:149], v[106:107], v[58:59], v[148:149]
	v_pk_fma_f32 v[146:147], v[108:109], v[60:61], v[146:147]
	v_pk_fma_f32 v[148:149], v[110:111], v[62:63], v[148:149]
	v_add_f32_e32 v150, v147, v146
	v_add_f32_e32 v151, v148, v149
	v_add_f32_e32 v64, v151, v150
	ds_read_b128 v[80:83], v196 offset:544
	ds_read_b128 v[84:87], v196 offset:560
	ds_read_b128 v[88:91], v196 offset:576
	ds_read_b128 v[92:95], v196 offset:592
	ds_read_b128 v[96:99], v196 offset:608
	ds_read_b128 v[100:103], v196 offset:624
	ds_read_b128 v[104:107], v196 offset:640
	s_waitcnt lgkmcnt(14)
	ds_read_b128 v[108:111], v196 offset:656
	s_waitcnt lgkmcnt(12)
	v_pk_fma_f32 v[146:147], v[112:113], v[32:33], v[200:201]
	v_pk_fma_f32 v[148:149], v[114:115], v[34:35], v[200:201]
	v_pk_fma_f32 v[146:147], v[116:117], v[36:37], v[146:147]
	v_pk_fma_f32 v[148:149], v[118:119], v[38:39], v[148:149]
	v_pk_fma_f32 v[146:147], v[120:121], v[40:41], v[146:147]
	v_pk_fma_f32 v[148:149], v[122:123], v[42:43], v[148:149]
	v_pk_fma_f32 v[146:147], v[124:125], v[44:45], v[146:147]
	v_pk_fma_f32 v[148:149], v[126:127], v[46:47], v[148:149]
	s_waitcnt lgkmcnt(8)
	v_pk_fma_f32 v[146:147], v[130:131], v[48:49], v[146:147]
	v_pk_fma_f32 v[148:149], v[132:133], v[50:51], v[148:149]
	v_pk_fma_f32 v[146:147], v[134:135], v[52:53], v[146:147]
	v_pk_fma_f32 v[148:149], v[136:137], v[54:55], v[148:149]
	v_pk_fma_f32 v[146:147], v[138:139], v[56:57], v[146:147]
	v_pk_fma_f32 v[148:149], v[140:141], v[58:59], v[148:149]
	v_pk_fma_f32 v[146:147], v[142:143], v[60:61], v[146:147]
	v_pk_fma_f32 v[148:149], v[144:145], v[62:63], v[148:149]
	v_add_f32_e32 v150, v147, v146
	v_add_f32_e32 v151, v148, v149
	v_add_f32_e32 v65, v151, v150
	ds_read_b128 v[112:115], v196 offset:816
	ds_read_b128 v[116:119], v196 offset:832
	ds_read_b128 v[120:123], v196 offset:848
	ds_read_b128 v[124:127], v196 offset:864
	ds_read_b128 v[130:133], v196 offset:880
	ds_read_b128 v[134:137], v196 offset:896
	ds_read_b128 v[138:141], v196 offset:912
	s_waitcnt lgkmcnt(14)
	ds_read_b128 v[142:145], v196 offset:928
	s_waitcnt lgkmcnt(12)
	v_pk_fma_f32 v[146:147], v[80:81], v[32:33], v[200:201]
	v_pk_fma_f32 v[148:149], v[82:83], v[34:35], v[200:201]
	v_pk_fma_f32 v[146:147], v[84:85], v[36:37], v[146:147]
	v_pk_fma_f32 v[148:149], v[86:87], v[38:39], v[148:149]
	v_pk_fma_f32 v[146:147], v[88:89], v[40:41], v[146:147]
	v_pk_fma_f32 v[148:149], v[90:91], v[42:43], v[148:149]
	v_pk_fma_f32 v[146:147], v[92:93], v[44:45], v[146:147]
	v_pk_fma_f32 v[148:149], v[94:95], v[46:47], v[148:149]
	s_waitcnt lgkmcnt(8)
	v_pk_fma_f32 v[146:147], v[96:97], v[48:49], v[146:147]
	v_pk_fma_f32 v[148:149], v[98:99], v[50:51], v[148:149]
	v_pk_fma_f32 v[146:147], v[100:101], v[52:53], v[146:147]
	v_pk_fma_f32 v[148:149], v[102:103], v[54:55], v[148:149]
	v_pk_fma_f32 v[146:147], v[104:105], v[56:57], v[146:147]
	v_pk_fma_f32 v[148:149], v[106:107], v[58:59], v[148:149]
	v_pk_fma_f32 v[146:147], v[108:109], v[60:61], v[146:147]
	v_pk_fma_f32 v[148:149], v[110:111], v[62:63], v[148:149]
	v_add_f32_e32 v150, v147, v146
	v_add_f32_e32 v151, v148, v149
	v_add_f32_e32 v66, v151, v150
	ds_read_b128 v[80:83], v196 offset:1088
	ds_read_b128 v[84:87], v196 offset:1104
	ds_read_b128 v[88:91], v196 offset:1120
	ds_read_b128 v[92:95], v196 offset:1136
	ds_read_b128 v[96:99], v196 offset:1152
	ds_read_b128 v[100:103], v196 offset:1168
	ds_read_b128 v[104:107], v196 offset:1184
	s_waitcnt lgkmcnt(14)
	ds_read_b128 v[108:111], v196 offset:1200
	s_waitcnt lgkmcnt(12)
	v_pk_fma_f32 v[146:147], v[112:113], v[32:33], v[200:201]
	v_pk_fma_f32 v[148:149], v[114:115], v[34:35], v[200:201]
	v_pk_fma_f32 v[146:147], v[116:117], v[36:37], v[146:147]
	v_pk_fma_f32 v[148:149], v[118:119], v[38:39], v[148:149]
	v_pk_fma_f32 v[146:147], v[120:121], v[40:41], v[146:147]
	v_pk_fma_f32 v[148:149], v[122:123], v[42:43], v[148:149]
	v_pk_fma_f32 v[146:147], v[124:125], v[44:45], v[146:147]
	v_pk_fma_f32 v[148:149], v[126:127], v[46:47], v[148:149]
	s_waitcnt lgkmcnt(8)
	v_pk_fma_f32 v[146:147], v[130:131], v[48:49], v[146:147]
	v_pk_fma_f32 v[148:149], v[132:133], v[50:51], v[148:149]
	v_pk_fma_f32 v[146:147], v[134:135], v[52:53], v[146:147]
	v_pk_fma_f32 v[148:149], v[136:137], v[54:55], v[148:149]
	v_pk_fma_f32 v[146:147], v[138:139], v[56:57], v[146:147]
	v_pk_fma_f32 v[148:149], v[140:141], v[58:59], v[148:149]
	v_pk_fma_f32 v[146:147], v[142:143], v[60:61], v[146:147]
	v_pk_fma_f32 v[148:149], v[144:145], v[62:63], v[148:149]
	v_add_f32_e32 v150, v147, v146
	v_add_f32_e32 v151, v148, v149
	v_add_f32_e32 v67, v151, v150
	ds_read_b128 v[112:115], v196 offset:1360
	ds_read_b128 v[116:119], v196 offset:1376
	ds_read_b128 v[120:123], v196 offset:1392
	ds_read_b128 v[124:127], v196 offset:1408
	ds_read_b128 v[130:133], v196 offset:1424
	ds_read_b128 v[134:137], v196 offset:1440
	ds_read_b128 v[138:141], v196 offset:1456
	s_waitcnt lgkmcnt(14)
	ds_read_b128 v[142:145], v196 offset:1472
	s_waitcnt lgkmcnt(12)
	v_pk_fma_f32 v[146:147], v[80:81], v[32:33], v[200:201]
	v_pk_fma_f32 v[148:149], v[82:83], v[34:35], v[200:201]
	v_pk_fma_f32 v[146:147], v[84:85], v[36:37], v[146:147]
	v_pk_fma_f32 v[148:149], v[86:87], v[38:39], v[148:149]
	v_pk_fma_f32 v[146:147], v[88:89], v[40:41], v[146:147]
	v_pk_fma_f32 v[148:149], v[90:91], v[42:43], v[148:149]
	v_pk_fma_f32 v[146:147], v[92:93], v[44:45], v[146:147]
	v_pk_fma_f32 v[148:149], v[94:95], v[46:47], v[148:149]
	s_waitcnt lgkmcnt(8)
	v_pk_fma_f32 v[146:147], v[96:97], v[48:49], v[146:147]
	v_pk_fma_f32 v[148:149], v[98:99], v[50:51], v[148:149]
	v_pk_fma_f32 v[146:147], v[100:101], v[52:53], v[146:147]
	v_pk_fma_f32 v[148:149], v[102:103], v[54:55], v[148:149]
	v_pk_fma_f32 v[146:147], v[104:105], v[56:57], v[146:147]
	v_pk_fma_f32 v[148:149], v[106:107], v[58:59], v[148:149]
	v_pk_fma_f32 v[146:147], v[108:109], v[60:61], v[146:147]
	v_pk_fma_f32 v[148:149], v[110:111], v[62:63], v[148:149]
	v_add_f32_e32 v150, v147, v146
	v_add_f32_e32 v151, v148, v149
	v_add_f32_e32 v68, v151, v150
	ds_read_b128 v[80:83], v196 offset:1632
	ds_read_b128 v[84:87], v196 offset:1648
	ds_read_b128 v[88:91], v196 offset:1664
	ds_read_b128 v[92:95], v196 offset:1680
	ds_read_b128 v[96:99], v196 offset:1696
	ds_read_b128 v[100:103], v196 offset:1712
	ds_read_b128 v[104:107], v196 offset:1728
	s_waitcnt lgkmcnt(14)
	ds_read_b128 v[108:111], v196 offset:1744
	s_waitcnt lgkmcnt(12)
	v_pk_fma_f32 v[146:147], v[112:113], v[32:33], v[200:201]
	v_pk_fma_f32 v[148:149], v[114:115], v[34:35], v[200:201]
	v_pk_fma_f32 v[146:147], v[116:117], v[36:37], v[146:147]
	v_pk_fma_f32 v[148:149], v[118:119], v[38:39], v[148:149]
	v_pk_fma_f32 v[146:147], v[120:121], v[40:41], v[146:147]
	v_pk_fma_f32 v[148:149], v[122:123], v[42:43], v[148:149]
	v_pk_fma_f32 v[146:147], v[124:125], v[44:45], v[146:147]
	v_pk_fma_f32 v[148:149], v[126:127], v[46:47], v[148:149]
	s_waitcnt lgkmcnt(8)
	v_pk_fma_f32 v[146:147], v[130:131], v[48:49], v[146:147]
	v_pk_fma_f32 v[148:149], v[132:133], v[50:51], v[148:149]
	v_pk_fma_f32 v[146:147], v[134:135], v[52:53], v[146:147]
	v_pk_fma_f32 v[148:149], v[136:137], v[54:55], v[148:149]
	v_pk_fma_f32 v[146:147], v[138:139], v[56:57], v[146:147]
	v_pk_fma_f32 v[148:149], v[140:141], v[58:59], v[148:149]
	v_pk_fma_f32 v[146:147], v[142:143], v[60:61], v[146:147]
	v_pk_fma_f32 v[148:149], v[144:145], v[62:63], v[148:149]
	v_add_f32_e32 v150, v147, v146
	v_add_f32_e32 v151, v148, v149
	v_add_f32_e32 v69, v151, v150
	ds_read_b128 v[112:115], v196 offset:1904
	ds_read_b128 v[116:119], v196 offset:1920
	ds_read_b128 v[120:123], v196 offset:1936
	ds_read_b128 v[124:127], v196 offset:1952
	ds_read_b128 v[130:133], v196 offset:1968
	ds_read_b128 v[134:137], v196 offset:1984
	ds_read_b128 v[138:141], v196 offset:2000
	s_waitcnt lgkmcnt(14)
	ds_read_b128 v[142:145], v196 offset:2016
	s_waitcnt lgkmcnt(12)
	v_pk_fma_f32 v[146:147], v[80:81], v[32:33], v[200:201]
	v_pk_fma_f32 v[148:149], v[82:83], v[34:35], v[200:201]
	v_pk_fma_f32 v[146:147], v[84:85], v[36:37], v[146:147]
	v_pk_fma_f32 v[148:149], v[86:87], v[38:39], v[148:149]
	v_pk_fma_f32 v[146:147], v[88:89], v[40:41], v[146:147]
	v_pk_fma_f32 v[148:149], v[90:91], v[42:43], v[148:149]
	v_pk_fma_f32 v[146:147], v[92:93], v[44:45], v[146:147]
	v_pk_fma_f32 v[148:149], v[94:95], v[46:47], v[148:149]
	s_waitcnt lgkmcnt(8)
	v_pk_fma_f32 v[146:147], v[96:97], v[48:49], v[146:147]
	v_pk_fma_f32 v[148:149], v[98:99], v[50:51], v[148:149]
	v_pk_fma_f32 v[146:147], v[100:101], v[52:53], v[146:147]
	v_pk_fma_f32 v[148:149], v[102:103], v[54:55], v[148:149]
	v_pk_fma_f32 v[146:147], v[104:105], v[56:57], v[146:147]
	v_pk_fma_f32 v[148:149], v[106:107], v[58:59], v[148:149]
	v_pk_fma_f32 v[146:147], v[108:109], v[60:61], v[146:147]
	v_pk_fma_f32 v[148:149], v[110:111], v[62:63], v[148:149]
	v_add_f32_e32 v150, v147, v146
	v_add_f32_e32 v151, v148, v149
	v_add_f32_e32 v70, v151, v150
	ds_read_b128 v[80:83], v196 offset:2176
	ds_read_b128 v[84:87], v196 offset:2192
	ds_read_b128 v[88:91], v196 offset:2208
	ds_read_b128 v[92:95], v196 offset:2224
	ds_read_b128 v[96:99], v196 offset:2240
	ds_read_b128 v[100:103], v196 offset:2256
	ds_read_b128 v[104:107], v196 offset:2272
	s_waitcnt lgkmcnt(14)
	ds_read_b128 v[108:111], v196 offset:2288
	s_waitcnt lgkmcnt(12)
	v_pk_fma_f32 v[146:147], v[112:113], v[32:33], v[200:201]
	v_pk_fma_f32 v[148:149], v[114:115], v[34:35], v[200:201]
	v_pk_fma_f32 v[146:147], v[116:117], v[36:37], v[146:147]
	v_pk_fma_f32 v[148:149], v[118:119], v[38:39], v[148:149]
	v_pk_fma_f32 v[146:147], v[120:121], v[40:41], v[146:147]
	v_pk_fma_f32 v[148:149], v[122:123], v[42:43], v[148:149]
	v_pk_fma_f32 v[146:147], v[124:125], v[44:45], v[146:147]
	v_pk_fma_f32 v[148:149], v[126:127], v[46:47], v[148:149]
	s_waitcnt lgkmcnt(8)
	v_pk_fma_f32 v[146:147], v[130:131], v[48:49], v[146:147]
	v_pk_fma_f32 v[148:149], v[132:133], v[50:51], v[148:149]
	v_pk_fma_f32 v[146:147], v[134:135], v[52:53], v[146:147]
	v_pk_fma_f32 v[148:149], v[136:137], v[54:55], v[148:149]
	v_pk_fma_f32 v[146:147], v[138:139], v[56:57], v[146:147]
	v_pk_fma_f32 v[148:149], v[140:141], v[58:59], v[148:149]
	v_pk_fma_f32 v[146:147], v[142:143], v[60:61], v[146:147]
	v_pk_fma_f32 v[148:149], v[144:145], v[62:63], v[148:149]
	v_add_f32_e32 v150, v147, v146
	v_add_f32_e32 v151, v148, v149
	v_add_f32_e32 v71, v151, v150
	ds_read_b128 v[112:115], v196 offset:2448
	ds_read_b128 v[116:119], v196 offset:2464
	ds_read_b128 v[120:123], v196 offset:2480
	ds_read_b128 v[124:127], v196 offset:2496
	ds_read_b128 v[130:133], v196 offset:2512
	ds_read_b128 v[134:137], v196 offset:2528
	ds_read_b128 v[138:141], v196 offset:2544
	s_waitcnt lgkmcnt(14)
	ds_read_b128 v[142:145], v196 offset:2560
	s_waitcnt lgkmcnt(12)
	v_pk_fma_f32 v[146:147], v[80:81], v[32:33], v[200:201]
	v_pk_fma_f32 v[148:149], v[82:83], v[34:35], v[200:201]
	v_pk_fma_f32 v[146:147], v[84:85], v[36:37], v[146:147]
	v_pk_fma_f32 v[148:149], v[86:87], v[38:39], v[148:149]
	v_pk_fma_f32 v[146:147], v[88:89], v[40:41], v[146:147]
	v_pk_fma_f32 v[148:149], v[90:91], v[42:43], v[148:149]
	v_pk_fma_f32 v[146:147], v[92:93], v[44:45], v[146:147]
	v_pk_fma_f32 v[148:149], v[94:95], v[46:47], v[148:149]
	s_waitcnt lgkmcnt(8)
	v_pk_fma_f32 v[146:147], v[96:97], v[48:49], v[146:147]
	v_pk_fma_f32 v[148:149], v[98:99], v[50:51], v[148:149]
	v_pk_fma_f32 v[146:147], v[100:101], v[52:53], v[146:147]
	v_pk_fma_f32 v[148:149], v[102:103], v[54:55], v[148:149]
	v_pk_fma_f32 v[146:147], v[104:105], v[56:57], v[146:147]
	v_pk_fma_f32 v[148:149], v[106:107], v[58:59], v[148:149]
	v_pk_fma_f32 v[146:147], v[108:109], v[60:61], v[146:147]
	v_pk_fma_f32 v[148:149], v[110:111], v[62:63], v[148:149]
	v_add_f32_e32 v150, v147, v146
	v_add_f32_e32 v151, v148, v149
	v_add_f32_e32 v72, v151, v150
	ds_read_b128 v[80:83], v196 offset:2720
	ds_read_b128 v[84:87], v196 offset:2736
	ds_read_b128 v[88:91], v196 offset:2752
	ds_read_b128 v[92:95], v196 offset:2768
	ds_read_b128 v[96:99], v196 offset:2784
	ds_read_b128 v[100:103], v196 offset:2800
	ds_read_b128 v[104:107], v196 offset:2816
	s_waitcnt lgkmcnt(14)
	ds_read_b128 v[108:111], v196 offset:2832
	s_waitcnt lgkmcnt(12)
	v_pk_fma_f32 v[146:147], v[112:113], v[32:33], v[200:201]
	v_pk_fma_f32 v[148:149], v[114:115], v[34:35], v[200:201]
	v_pk_fma_f32 v[146:147], v[116:117], v[36:37], v[146:147]
	v_pk_fma_f32 v[148:149], v[118:119], v[38:39], v[148:149]
	v_pk_fma_f32 v[146:147], v[120:121], v[40:41], v[146:147]
	v_pk_fma_f32 v[148:149], v[122:123], v[42:43], v[148:149]
	v_pk_fma_f32 v[146:147], v[124:125], v[44:45], v[146:147]
	v_pk_fma_f32 v[148:149], v[126:127], v[46:47], v[148:149]
	s_waitcnt lgkmcnt(8)
	v_pk_fma_f32 v[146:147], v[130:131], v[48:49], v[146:147]
	v_pk_fma_f32 v[148:149], v[132:133], v[50:51], v[148:149]
	v_pk_fma_f32 v[146:147], v[134:135], v[52:53], v[146:147]
	v_pk_fma_f32 v[148:149], v[136:137], v[54:55], v[148:149]
	v_pk_fma_f32 v[146:147], v[138:139], v[56:57], v[146:147]
	v_pk_fma_f32 v[148:149], v[140:141], v[58:59], v[148:149]
	v_pk_fma_f32 v[146:147], v[142:143], v[60:61], v[146:147]
	v_pk_fma_f32 v[148:149], v[144:145], v[62:63], v[148:149]
	v_add_f32_e32 v150, v147, v146
	v_add_f32_e32 v151, v148, v149
	v_add_f32_e32 v73, v151, v150
	ds_read_b128 v[112:115], v196 offset:2992
	ds_read_b128 v[116:119], v196 offset:3008
	ds_read_b128 v[120:123], v196 offset:3024
	ds_read_b128 v[124:127], v196 offset:3040
	ds_read_b128 v[130:133], v196 offset:3056
	ds_read_b128 v[134:137], v196 offset:3072
	ds_read_b128 v[138:141], v196 offset:3088
	s_waitcnt lgkmcnt(14)
	ds_read_b128 v[142:145], v196 offset:3104
	s_waitcnt lgkmcnt(12)
	v_pk_fma_f32 v[146:147], v[80:81], v[32:33], v[200:201]
	v_pk_fma_f32 v[148:149], v[82:83], v[34:35], v[200:201]
	v_pk_fma_f32 v[146:147], v[84:85], v[36:37], v[146:147]
	v_pk_fma_f32 v[148:149], v[86:87], v[38:39], v[148:149]
	v_pk_fma_f32 v[146:147], v[88:89], v[40:41], v[146:147]
	v_pk_fma_f32 v[148:149], v[90:91], v[42:43], v[148:149]
	v_pk_fma_f32 v[146:147], v[92:93], v[44:45], v[146:147]
	v_pk_fma_f32 v[148:149], v[94:95], v[46:47], v[148:149]
	s_waitcnt lgkmcnt(8)
	v_pk_fma_f32 v[146:147], v[96:97], v[48:49], v[146:147]
	v_pk_fma_f32 v[148:149], v[98:99], v[50:51], v[148:149]
	v_pk_fma_f32 v[146:147], v[100:101], v[52:53], v[146:147]
	v_pk_fma_f32 v[148:149], v[102:103], v[54:55], v[148:149]
	v_pk_fma_f32 v[146:147], v[104:105], v[56:57], v[146:147]
	v_pk_fma_f32 v[148:149], v[106:107], v[58:59], v[148:149]
	v_pk_fma_f32 v[146:147], v[108:109], v[60:61], v[146:147]
	v_pk_fma_f32 v[148:149], v[110:111], v[62:63], v[148:149]
	v_add_f32_e32 v150, v147, v146
	v_add_f32_e32 v151, v148, v149
	v_add_f32_e32 v74, v151, v150
	ds_read_b128 v[80:83], v196 offset:3264
	ds_read_b128 v[84:87], v196 offset:3280
	ds_read_b128 v[88:91], v196 offset:3296
	ds_read_b128 v[92:95], v196 offset:3312
	ds_read_b128 v[96:99], v196 offset:3328
	ds_read_b128 v[100:103], v196 offset:3344
	ds_read_b128 v[104:107], v196 offset:3360
	s_waitcnt lgkmcnt(14)
	ds_read_b128 v[108:111], v196 offset:3376
	s_waitcnt lgkmcnt(12)
	v_pk_fma_f32 v[146:147], v[112:113], v[32:33], v[200:201]
	v_pk_fma_f32 v[148:149], v[114:115], v[34:35], v[200:201]
	v_pk_fma_f32 v[146:147], v[116:117], v[36:37], v[146:147]
	v_pk_fma_f32 v[148:149], v[118:119], v[38:39], v[148:149]
	v_pk_fma_f32 v[146:147], v[120:121], v[40:41], v[146:147]
	v_pk_fma_f32 v[148:149], v[122:123], v[42:43], v[148:149]
	v_pk_fma_f32 v[146:147], v[124:125], v[44:45], v[146:147]
	v_pk_fma_f32 v[148:149], v[126:127], v[46:47], v[148:149]
	s_waitcnt lgkmcnt(8)
	v_pk_fma_f32 v[146:147], v[130:131], v[48:49], v[146:147]
	v_pk_fma_f32 v[148:149], v[132:133], v[50:51], v[148:149]
	v_pk_fma_f32 v[146:147], v[134:135], v[52:53], v[146:147]
	v_pk_fma_f32 v[148:149], v[136:137], v[54:55], v[148:149]
	v_pk_fma_f32 v[146:147], v[138:139], v[56:57], v[146:147]
	v_pk_fma_f32 v[148:149], v[140:141], v[58:59], v[148:149]
	v_pk_fma_f32 v[146:147], v[142:143], v[60:61], v[146:147]
	v_pk_fma_f32 v[148:149], v[144:145], v[62:63], v[148:149]
	v_add_f32_e32 v150, v147, v146
	v_add_f32_e32 v151, v148, v149
	v_add_f32_e32 v75, v151, v150
	ds_read_b128 v[112:115], v196 offset:3536
	ds_read_b128 v[116:119], v196 offset:3552
	ds_read_b128 v[120:123], v196 offset:3568
	ds_read_b128 v[124:127], v196 offset:3584
	ds_read_b128 v[130:133], v196 offset:3600
	ds_read_b128 v[134:137], v196 offset:3616
	ds_read_b128 v[138:141], v196 offset:3632
	s_waitcnt lgkmcnt(14)
	ds_read_b128 v[142:145], v196 offset:3648
	s_waitcnt lgkmcnt(12)
	v_pk_fma_f32 v[146:147], v[80:81], v[32:33], v[200:201]
	v_pk_fma_f32 v[148:149], v[82:83], v[34:35], v[200:201]
	v_pk_fma_f32 v[146:147], v[84:85], v[36:37], v[146:147]
	v_pk_fma_f32 v[148:149], v[86:87], v[38:39], v[148:149]
	v_pk_fma_f32 v[146:147], v[88:89], v[40:41], v[146:147]
	v_pk_fma_f32 v[148:149], v[90:91], v[42:43], v[148:149]
	v_pk_fma_f32 v[146:147], v[92:93], v[44:45], v[146:147]
	v_pk_fma_f32 v[148:149], v[94:95], v[46:47], v[148:149]
	s_waitcnt lgkmcnt(8)
	v_pk_fma_f32 v[146:147], v[96:97], v[48:49], v[146:147]
	v_pk_fma_f32 v[148:149], v[98:99], v[50:51], v[148:149]
	v_pk_fma_f32 v[146:147], v[100:101], v[52:53], v[146:147]
	v_pk_fma_f32 v[148:149], v[102:103], v[54:55], v[148:149]
	v_pk_fma_f32 v[146:147], v[104:105], v[56:57], v[146:147]
	v_pk_fma_f32 v[148:149], v[106:107], v[58:59], v[148:149]
	v_pk_fma_f32 v[146:147], v[108:109], v[60:61], v[146:147]
	v_pk_fma_f32 v[148:149], v[110:111], v[62:63], v[148:149]
	v_add_f32_e32 v150, v147, v146
	v_add_f32_e32 v151, v148, v149
	v_add_f32_e32 v76, v151, v150
	ds_read_b128 v[80:83], v196 offset:3808
	ds_read_b128 v[84:87], v196 offset:3824
	ds_read_b128 v[88:91], v196 offset:3840
	ds_read_b128 v[92:95], v196 offset:3856
	ds_read_b128 v[96:99], v196 offset:3872
	ds_read_b128 v[100:103], v196 offset:3888
	ds_read_b128 v[104:107], v196 offset:3904
	s_waitcnt lgkmcnt(14)
	ds_read_b128 v[108:111], v196 offset:3920
	s_waitcnt lgkmcnt(12)
	v_pk_fma_f32 v[146:147], v[112:113], v[32:33], v[200:201]
	v_pk_fma_f32 v[148:149], v[114:115], v[34:35], v[200:201]
	v_pk_fma_f32 v[146:147], v[116:117], v[36:37], v[146:147]
	v_pk_fma_f32 v[148:149], v[118:119], v[38:39], v[148:149]
	v_pk_fma_f32 v[146:147], v[120:121], v[40:41], v[146:147]
	v_pk_fma_f32 v[148:149], v[122:123], v[42:43], v[148:149]
	v_pk_fma_f32 v[146:147], v[124:125], v[44:45], v[146:147]
	v_pk_fma_f32 v[148:149], v[126:127], v[46:47], v[148:149]
	s_waitcnt lgkmcnt(8)
	v_pk_fma_f32 v[146:147], v[130:131], v[48:49], v[146:147]
	v_pk_fma_f32 v[148:149], v[132:133], v[50:51], v[148:149]
	v_pk_fma_f32 v[146:147], v[134:135], v[52:53], v[146:147]
	v_pk_fma_f32 v[148:149], v[136:137], v[54:55], v[148:149]
	v_pk_fma_f32 v[146:147], v[138:139], v[56:57], v[146:147]
	v_pk_fma_f32 v[148:149], v[140:141], v[58:59], v[148:149]
	v_pk_fma_f32 v[146:147], v[142:143], v[60:61], v[146:147]
	v_pk_fma_f32 v[148:149], v[144:145], v[62:63], v[148:149]
	v_add_f32_e32 v150, v147, v146
	v_add_f32_e32 v151, v148, v149
	v_add_f32_e32 v77, v151, v150
	ds_read_b128 v[112:115], v196 offset:4080
	ds_read_b128 v[116:119], v196 offset:4096
	ds_read_b128 v[120:123], v196 offset:4112
	ds_read_b128 v[124:127], v196 offset:4128
	ds_read_b128 v[130:133], v196 offset:4144
	ds_read_b128 v[134:137], v196 offset:4160
	ds_read_b128 v[138:141], v196 offset:4176
	s_waitcnt lgkmcnt(14)
	ds_read_b128 v[142:145], v196 offset:4192
	s_waitcnt lgkmcnt(12)
	v_pk_fma_f32 v[146:147], v[80:81], v[32:33], v[200:201]
	v_pk_fma_f32 v[148:149], v[82:83], v[34:35], v[200:201]
	v_pk_fma_f32 v[146:147], v[84:85], v[36:37], v[146:147]
	v_pk_fma_f32 v[148:149], v[86:87], v[38:39], v[148:149]
	v_pk_fma_f32 v[146:147], v[88:89], v[40:41], v[146:147]
	v_pk_fma_f32 v[148:149], v[90:91], v[42:43], v[148:149]
	v_pk_fma_f32 v[146:147], v[92:93], v[44:45], v[146:147]
	v_pk_fma_f32 v[148:149], v[94:95], v[46:47], v[148:149]
	s_waitcnt lgkmcnt(8)
	v_pk_fma_f32 v[146:147], v[96:97], v[48:49], v[146:147]
	v_pk_fma_f32 v[148:149], v[98:99], v[50:51], v[148:149]
	v_pk_fma_f32 v[146:147], v[100:101], v[52:53], v[146:147]
	v_pk_fma_f32 v[148:149], v[102:103], v[54:55], v[148:149]
	v_pk_fma_f32 v[146:147], v[104:105], v[56:57], v[146:147]
	v_pk_fma_f32 v[148:149], v[106:107], v[58:59], v[148:149]
	v_pk_fma_f32 v[146:147], v[108:109], v[60:61], v[146:147]
	v_pk_fma_f32 v[148:149], v[110:111], v[62:63], v[148:149]
	v_add_f32_e32 v150, v147, v146
	v_add_f32_e32 v151, v148, v149
	v_add_f32_e32 v78, v151, v150
	s_waitcnt lgkmcnt(4)
	v_pk_fma_f32 v[146:147], v[112:113], v[32:33], v[200:201]
	v_pk_fma_f32 v[148:149], v[114:115], v[34:35], v[200:201]
	v_pk_fma_f32 v[146:147], v[116:117], v[36:37], v[146:147]
	v_pk_fma_f32 v[148:149], v[118:119], v[38:39], v[148:149]
	v_pk_fma_f32 v[146:147], v[120:121], v[40:41], v[146:147]
	v_pk_fma_f32 v[148:149], v[122:123], v[42:43], v[148:149]
	v_pk_fma_f32 v[146:147], v[124:125], v[44:45], v[146:147]
	v_pk_fma_f32 v[148:149], v[126:127], v[46:47], v[148:149]
	s_waitcnt lgkmcnt(0)
	v_pk_fma_f32 v[146:147], v[130:131], v[48:49], v[146:147]
	v_pk_fma_f32 v[148:149], v[132:133], v[50:51], v[148:149]
	v_pk_fma_f32 v[146:147], v[134:135], v[52:53], v[146:147]
	v_pk_fma_f32 v[148:149], v[136:137], v[54:55], v[148:149]
	v_pk_fma_f32 v[146:147], v[138:139], v[56:57], v[146:147]
	v_pk_fma_f32 v[148:149], v[140:141], v[58:59], v[148:149]
	v_pk_fma_f32 v[146:147], v[142:143], v[60:61], v[146:147]
	v_pk_fma_f32 v[148:149], v[144:145], v[62:63], v[148:149]
	v_add_f32_e32 v150, v147, v146
	v_add_f32_e32 v151, v148, v149
	v_add_f32_e32 v79, v151, v150
	v_mov_b32_e32 v154, v64
	v_mov_b32_e32 v155, v65
	s_nop 1
	v_permlane32_swap_b32_e32 v64, v154
	v_permlane32_swap_b32_e32 v65, v155
	v_mov_b32_e32 v156, v66
	v_mov_b32_e32 v157, v67
	s_nop 1
	v_permlane32_swap_b32_e32 v66, v156
	v_permlane32_swap_b32_e32 v67, v157
	v_mov_b32_e32 v158, v68
	v_mov_b32_e32 v159, v69
	s_nop 1
	v_permlane32_swap_b32_e32 v68, v158
	v_permlane32_swap_b32_e32 v69, v159
	v_mov_b32_e32 v160, v70
	v_mov_b32_e32 v161, v71
	s_nop 1
	v_permlane32_swap_b32_e32 v70, v160
	v_permlane32_swap_b32_e32 v71, v161
	v_mov_b32_e32 v162, v72
	v_mov_b32_e32 v163, v73
	s_nop 1
	v_permlane32_swap_b32_e32 v72, v162
	v_permlane32_swap_b32_e32 v73, v163
	v_mov_b32_e32 v164, v74
	v_mov_b32_e32 v165, v75
	s_nop 1
	v_permlane32_swap_b32_e32 v74, v164
	v_permlane32_swap_b32_e32 v75, v165
	v_mov_b32_e32 v166, v76
	v_mov_b32_e32 v167, v77
	s_nop 1
	v_permlane32_swap_b32_e32 v76, v166
	v_permlane32_swap_b32_e32 v77, v167
	v_mov_b32_e32 v168, v78
	v_mov_b32_e32 v169, v79
	s_nop 1
	v_permlane32_swap_b32_e32 v78, v168
	v_permlane32_swap_b32_e32 v79, v169
	ds_read_b128 v[80:83], v197 offset:0
	ds_read_b128 v[84:87], v197 offset:16
	ds_read_b128 v[88:91], v197 offset:32
	ds_read_b128 v[92:95], v197 offset:48
	ds_read_b128 v[96:99], v197 offset:64
	ds_read_b128 v[100:103], v197 offset:80
	ds_read_b128 v[104:107], v197 offset:96
	ds_read_b128 v[108:111], v197 offset:112
	ds_read_b128 v[112:115], v197 offset:128
	ds_read_b128 v[116:119], v197 offset:144
	ds_read_b128 v[120:123], v197 offset:160
	ds_read_b128 v[124:127], v197 offset:176
	ds_read_b128 v[130:133], v197 offset:192
	ds_read_b128 v[134:137], v197 offset:208
	ds_read_b128 v[138:141], v197 offset:224
	s_waitcnt lgkmcnt(14)
	ds_read_b128 v[142:145], v197 offset:240
	s_waitcnt lgkmcnt(12)
	v_pk_fma_f32 v[146:147], v[80:81], v[64:65], v[200:201] neg_lo:[1,0,0] neg_hi:[1,0,0]
	v_pk_fma_f32 v[148:149], v[82:83], v[66:67], v[200:201] neg_lo:[1,0,0] neg_hi:[1,0,0]
	v_pk_fma_f32 v[146:147], v[84:85], v[68:69], v[146:147] neg_lo:[1,0,0] neg_hi:[1,0,0]
	v_pk_fma_f32 v[148:149], v[86:87], v[70:71], v[148:149] neg_lo:[1,0,0] neg_hi:[1,0,0]
	v_pk_fma_f32 v[146:147], v[88:89], v[72:73], v[146:147] neg_lo:[1,0,0] neg_hi:[1,0,0]
	v_pk_fma_f32 v[148:149], v[90:91], v[74:75], v[148:149] neg_lo:[1,0,0] neg_hi:[1,0,0]
	v_pk_fma_f32 v[146:147], v[92:93], v[76:77], v[146:147] neg_lo:[1,0,0] neg_hi:[1,0,0]
	v_pk_fma_f32 v[148:149], v[94:95], v[78:79], v[148:149] neg_lo:[1,0,0] neg_hi:[1,0,0]
	s_waitcnt lgkmcnt(8)
	v_pk_fma_f32 v[146:147], v[96:97], v[154:155], v[146:147] neg_lo:[1,0,0] neg_hi:[1,0,0]
	v_pk_fma_f32 v[148:149], v[98:99], v[156:157], v[148:149] neg_lo:[1,0,0] neg_hi:[1,0,0]
	v_pk_fma_f32 v[146:147], v[100:101], v[158:159], v[146:147] neg_lo:[1,0,0] neg_hi:[1,0,0]
	v_pk_fma_f32 v[148:149], v[102:103], v[160:161], v[148:149] neg_lo:[1,0,0] neg_hi:[1,0,0]
	v_pk_fma_f32 v[146:147], v[104:105], v[162:163], v[146:147] neg_lo:[1,0,0] neg_hi:[1,0,0]
	v_pk_fma_f32 v[148:149], v[106:107], v[164:165], v[148:149] neg_lo:[1,0,0] neg_hi:[1,0,0]
	v_pk_fma_f32 v[146:147], v[108:109], v[166:167], v[146:147] neg_lo:[1,0,0] neg_hi:[1,0,0]
	v_pk_fma_f32 v[148:149], v[110:111], v[168:169], v[148:149] neg_lo:[1,0,0] neg_hi:[1,0,0]
	v_add_f32_e32 v150, v147, v146
	v_add_f32_e32 v151, v148, v149
	v_add_f32_e32 v170, v151, v150
	ds_read_b128 v[80:83], v197 offset:256
	ds_read_b128 v[84:87], v197 offset:272
	ds_read_b128 v[88:91], v197 offset:288
	ds_read_b128 v[92:95], v197 offset:304
	ds_read_b128 v[96:99], v197 offset:320
	ds_read_b128 v[100:103], v197 offset:336
	ds_read_b128 v[104:107], v197 offset:352
	s_waitcnt lgkmcnt(14)
	ds_read_b128 v[108:111], v197 offset:368
	s_waitcnt lgkmcnt(12)
	v_pk_fma_f32 v[146:147], v[112:113], v[64:65], v[200:201] neg_lo:[1,0,0] neg_hi:[1,0,0]
	v_pk_fma_f32 v[148:149], v[114:115], v[66:67], v[200:201] neg_lo:[1,0,0] neg_hi:[1,0,0]
	v_pk_fma_f32 v[146:147], v[116:117], v[68:69], v[146:147] neg_lo:[1,0,0] neg_hi:[1,0,0]
	v_pk_fma_f32 v[148:149], v[118:119], v[70:71], v[148:149] neg_lo:[1,0,0] neg_hi:[1,0,0]
	v_pk_fma_f32 v[146:147], v[120:121], v[72:73], v[146:147] neg_lo:[1,0,0] neg_hi:[1,0,0]
	v_pk_fma_f32 v[148:149], v[122:123], v[74:75], v[148:149] neg_lo:[1,0,0] neg_hi:[1,0,0]
	v_pk_fma_f32 v[146:147], v[124:125], v[76:77], v[146:147] neg_lo:[1,0,0] neg_hi:[1,0,0]
	v_pk_fma_f32 v[148:149], v[126:127], v[78:79], v[148:149] neg_lo:[1,0,0] neg_hi:[1,0,0]
	s_waitcnt lgkmcnt(8)
	v_pk_fma_f32 v[146:147], v[130:131], v[154:155], v[146:147] neg_lo:[1,0,0] neg_hi:[1,0,0]
	v_pk_fma_f32 v[148:149], v[132:133], v[156:157], v[148:149] neg_lo:[1,0,0] neg_hi:[1,0,0]
	v_pk_fma_f32 v[146:147], v[134:135], v[158:159], v[146:147] neg_lo:[1,0,0] neg_hi:[1,0,0]
	v_pk_fma_f32 v[148:149], v[136:137], v[160:161], v[148:149] neg_lo:[1,0,0] neg_hi:[1,0,0]
	v_pk_fma_f32 v[146:147], v[138:139], v[162:163], v[146:147] neg_lo:[1,0,0] neg_hi:[1,0,0]
	v_pk_fma_f32 v[148:149], v[140:141], v[164:165], v[148:149] neg_lo:[1,0,0] neg_hi:[1,0,0]
	v_pk_fma_f32 v[146:147], v[142:143], v[166:167], v[146:147] neg_lo:[1,0,0] neg_hi:[1,0,0]
	v_pk_fma_f32 v[148:149], v[144:145], v[168:169], v[148:149] neg_lo:[1,0,0] neg_hi:[1,0,0]
	v_add_f32_e32 v150, v147, v146
	v_add_f32_e32 v151, v148, v149
	v_add_f32_e32 v171, v151, v150
	ds_read_b128 v[112:115], v197 offset:384
	ds_read_b128 v[116:119], v197 offset:400
	ds_read_b128 v[120:123], v197 offset:416
	ds_read_b128 v[124:127], v197 offset:432
	ds_read_b128 v[130:133], v197 offset:448
	ds_read_b128 v[134:137], v197 offset:464
	ds_read_b128 v[138:141], v197 offset:480
	s_waitcnt lgkmcnt(14)
	ds_read_b128 v[142:145], v197 offset:496
	s_waitcnt lgkmcnt(12)
	v_pk_fma_f32 v[146:147], v[80:81], v[64:65], v[200:201] neg_lo:[1,0,0] neg_hi:[1,0,0]
	v_pk_fma_f32 v[148:149], v[82:83], v[66:67], v[200:201] neg_lo:[1,0,0] neg_hi:[1,0,0]
	v_pk_fma_f32 v[146:147], v[84:85], v[68:69], v[146:147] neg_lo:[1,0,0] neg_hi:[1,0,0]
	v_pk_fma_f32 v[148:149], v[86:87], v[70:71], v[148:149] neg_lo:[1,0,0] neg_hi:[1,0,0]
	v_pk_fma_f32 v[146:147], v[88:89], v[72:73], v[146:147] neg_lo:[1,0,0] neg_hi:[1,0,0]
	v_pk_fma_f32 v[148:149], v[90:91], v[74:75], v[148:149] neg_lo:[1,0,0] neg_hi:[1,0,0]
	v_pk_fma_f32 v[146:147], v[92:93], v[76:77], v[146:147] neg_lo:[1,0,0] neg_hi:[1,0,0]
	v_pk_fma_f32 v[148:149], v[94:95], v[78:79], v[148:149] neg_lo:[1,0,0] neg_hi:[1,0,0]
	s_waitcnt lgkmcnt(8)
	v_pk_fma_f32 v[146:147], v[96:97], v[154:155], v[146:147] neg_lo:[1,0,0] neg_hi:[1,0,0]
	v_pk_fma_f32 v[148:149], v[98:99], v[156:157], v[148:149] neg_lo:[1,0,0] neg_hi:[1,0,0]
	v_pk_fma_f32 v[146:147], v[100:101], v[158:159], v[146:147] neg_lo:[1,0,0] neg_hi:[1,0,0]
	v_pk_fma_f32 v[148:149], v[102:103], v[160:161], v[148:149] neg_lo:[1,0,0] neg_hi:[1,0,0]
	v_pk_fma_f32 v[146:147], v[104:105], v[162:163], v[146:147] neg_lo:[1,0,0] neg_hi:[1,0,0]
	v_pk_fma_f32 v[148:149], v[106:107], v[164:165], v[148:149] neg_lo:[1,0,0] neg_hi:[1,0,0]
	v_pk_fma_f32 v[146:147], v[108:109], v[166:167], v[146:147] neg_lo:[1,0,0] neg_hi:[1,0,0]
	v_pk_fma_f32 v[148:149], v[110:111], v[168:169], v[148:149] neg_lo:[1,0,0] neg_hi:[1,0,0]
	v_add_f32_e32 v150, v147, v146
	v_add_f32_e32 v151, v148, v149
	v_add_f32_e32 v172, v151, v150
	ds_read_b128 v[80:83], v197 offset:512
	ds_read_b128 v[84:87], v197 offset:528
	ds_read_b128 v[88:91], v197 offset:544
	ds_read_b128 v[92:95], v197 offset:560
	ds_read_b128 v[96:99], v197 offset:576
	ds_read_b128 v[100:103], v197 offset:592
	ds_read_b128 v[104:107], v197 offset:608
	s_waitcnt lgkmcnt(14)
	ds_read_b128 v[108:111], v197 offset:624
	s_waitcnt lgkmcnt(12)
	v_pk_fma_f32 v[146:147], v[112:113], v[64:65], v[200:201] neg_lo:[1,0,0] neg_hi:[1,0,0]
	v_pk_fma_f32 v[148:149], v[114:115], v[66:67], v[200:201] neg_lo:[1,0,0] neg_hi:[1,0,0]
	v_pk_fma_f32 v[146:147], v[116:117], v[68:69], v[146:147] neg_lo:[1,0,0] neg_hi:[1,0,0]
	v_pk_fma_f32 v[148:149], v[118:119], v[70:71], v[148:149] neg_lo:[1,0,0] neg_hi:[1,0,0]
	v_pk_fma_f32 v[146:147], v[120:121], v[72:73], v[146:147] neg_lo:[1,0,0] neg_hi:[1,0,0]
	v_pk_fma_f32 v[148:149], v[122:123], v[74:75], v[148:149] neg_lo:[1,0,0] neg_hi:[1,0,0]
	v_pk_fma_f32 v[146:147], v[124:125], v[76:77], v[146:147] neg_lo:[1,0,0] neg_hi:[1,0,0]
	v_pk_fma_f32 v[148:149], v[126:127], v[78:79], v[148:149] neg_lo:[1,0,0] neg_hi:[1,0,0]
	s_waitcnt lgkmcnt(8)
	v_pk_fma_f32 v[146:147], v[130:131], v[154:155], v[146:147] neg_lo:[1,0,0] neg_hi:[1,0,0]
	v_pk_fma_f32 v[148:149], v[132:133], v[156:157], v[148:149] neg_lo:[1,0,0] neg_hi:[1,0,0]
	v_pk_fma_f32 v[146:147], v[134:135], v[158:159], v[146:147] neg_lo:[1,0,0] neg_hi:[1,0,0]
	v_pk_fma_f32 v[148:149], v[136:137], v[160:161], v[148:149] neg_lo:[1,0,0] neg_hi:[1,0,0]
	v_pk_fma_f32 v[146:147], v[138:139], v[162:163], v[146:147] neg_lo:[1,0,0] neg_hi:[1,0,0]
	v_pk_fma_f32 v[148:149], v[140:141], v[164:165], v[148:149] neg_lo:[1,0,0] neg_hi:[1,0,0]
	v_pk_fma_f32 v[146:147], v[142:143], v[166:167], v[146:147] neg_lo:[1,0,0] neg_hi:[1,0,0]
	v_pk_fma_f32 v[148:149], v[144:145], v[168:169], v[148:149] neg_lo:[1,0,0] neg_hi:[1,0,0]
	v_add_f32_e32 v150, v147, v146
	v_add_f32_e32 v151, v148, v149
	v_add_f32_e32 v173, v151, v150
	ds_read_b128 v[112:115], v197 offset:640
	ds_read_b128 v[116:119], v197 offset:656
	ds_read_b128 v[120:123], v197 offset:672
	ds_read_b128 v[124:127], v197 offset:688
	ds_read_b128 v[130:133], v197 offset:704
	ds_read_b128 v[134:137], v197 offset:720
	ds_read_b128 v[138:141], v197 offset:736
	s_waitcnt lgkmcnt(14)
	ds_read_b128 v[142:145], v197 offset:752
	s_waitcnt lgkmcnt(12)
	v_pk_fma_f32 v[146:147], v[80:81], v[64:65], v[200:201] neg_lo:[1,0,0] neg_hi:[1,0,0]
	v_pk_fma_f32 v[148:149], v[82:83], v[66:67], v[200:201] neg_lo:[1,0,0] neg_hi:[1,0,0]
	v_pk_fma_f32 v[146:147], v[84:85], v[68:69], v[146:147] neg_lo:[1,0,0] neg_hi:[1,0,0]
	v_pk_fma_f32 v[148:149], v[86:87], v[70:71], v[148:149] neg_lo:[1,0,0] neg_hi:[1,0,0]
	v_pk_fma_f32 v[146:147], v[88:89], v[72:73], v[146:147] neg_lo:[1,0,0] neg_hi:[1,0,0]
	v_pk_fma_f32 v[148:149], v[90:91], v[74:75], v[148:149] neg_lo:[1,0,0] neg_hi:[1,0,0]
	v_pk_fma_f32 v[146:147], v[92:93], v[76:77], v[146:147] neg_lo:[1,0,0] neg_hi:[1,0,0]
	v_pk_fma_f32 v[148:149], v[94:95], v[78:79], v[148:149] neg_lo:[1,0,0] neg_hi:[1,0,0]
	s_waitcnt lgkmcnt(8)
	v_pk_fma_f32 v[146:147], v[96:97], v[154:155], v[146:147] neg_lo:[1,0,0] neg_hi:[1,0,0]
	v_pk_fma_f32 v[148:149], v[98:99], v[156:157], v[148:149] neg_lo:[1,0,0] neg_hi:[1,0,0]
	v_pk_fma_f32 v[146:147], v[100:101], v[158:159], v[146:147] neg_lo:[1,0,0] neg_hi:[1,0,0]
	v_pk_fma_f32 v[148:149], v[102:103], v[160:161], v[148:149] neg_lo:[1,0,0] neg_hi:[1,0,0]
	v_pk_fma_f32 v[146:147], v[104:105], v[162:163], v[146:147] neg_lo:[1,0,0] neg_hi:[1,0,0]
	v_pk_fma_f32 v[148:149], v[106:107], v[164:165], v[148:149] neg_lo:[1,0,0] neg_hi:[1,0,0]
	v_pk_fma_f32 v[146:147], v[108:109], v[166:167], v[146:147] neg_lo:[1,0,0] neg_hi:[1,0,0]
	v_pk_fma_f32 v[148:149], v[110:111], v[168:169], v[148:149] neg_lo:[1,0,0] neg_hi:[1,0,0]
	v_add_f32_e32 v150, v147, v146
	v_add_f32_e32 v151, v148, v149
	v_add_f32_e32 v174, v151, v150
	ds_read_b128 v[80:83], v197 offset:768
	ds_read_b128 v[84:87], v197 offset:784
	ds_read_b128 v[88:91], v197 offset:800
	ds_read_b128 v[92:95], v197 offset:816
	ds_read_b128 v[96:99], v197 offset:832
	ds_read_b128 v[100:103], v197 offset:848
	ds_read_b128 v[104:107], v197 offset:864
	s_waitcnt lgkmcnt(14)
	ds_read_b128 v[108:111], v197 offset:880
	s_waitcnt lgkmcnt(12)
	v_pk_fma_f32 v[146:147], v[112:113], v[64:65], v[200:201] neg_lo:[1,0,0] neg_hi:[1,0,0]
	v_pk_fma_f32 v[148:149], v[114:115], v[66:67], v[200:201] neg_lo:[1,0,0] neg_hi:[1,0,0]
	v_pk_fma_f32 v[146:147], v[116:117], v[68:69], v[146:147] neg_lo:[1,0,0] neg_hi:[1,0,0]
	v_pk_fma_f32 v[148:149], v[118:119], v[70:71], v[148:149] neg_lo:[1,0,0] neg_hi:[1,0,0]
	v_pk_fma_f32 v[146:147], v[120:121], v[72:73], v[146:147] neg_lo:[1,0,0] neg_hi:[1,0,0]
	v_pk_fma_f32 v[148:149], v[122:123], v[74:75], v[148:149] neg_lo:[1,0,0] neg_hi:[1,0,0]
	v_pk_fma_f32 v[146:147], v[124:125], v[76:77], v[146:147] neg_lo:[1,0,0] neg_hi:[1,0,0]
	v_pk_fma_f32 v[148:149], v[126:127], v[78:79], v[148:149] neg_lo:[1,0,0] neg_hi:[1,0,0]
	s_waitcnt lgkmcnt(8)
	v_pk_fma_f32 v[146:147], v[130:131], v[154:155], v[146:147] neg_lo:[1,0,0] neg_hi:[1,0,0]
	v_pk_fma_f32 v[148:149], v[132:133], v[156:157], v[148:149] neg_lo:[1,0,0] neg_hi:[1,0,0]
	v_pk_fma_f32 v[146:147], v[134:135], v[158:159], v[146:147] neg_lo:[1,0,0] neg_hi:[1,0,0]
	v_pk_fma_f32 v[148:149], v[136:137], v[160:161], v[148:149] neg_lo:[1,0,0] neg_hi:[1,0,0]
	v_pk_fma_f32 v[146:147], v[138:139], v[162:163], v[146:147] neg_lo:[1,0,0] neg_hi:[1,0,0]
	v_pk_fma_f32 v[148:149], v[140:141], v[164:165], v[148:149] neg_lo:[1,0,0] neg_hi:[1,0,0]
	v_pk_fma_f32 v[146:147], v[142:143], v[166:167], v[146:147] neg_lo:[1,0,0] neg_hi:[1,0,0]
	v_pk_fma_f32 v[148:149], v[144:145], v[168:169], v[148:149] neg_lo:[1,0,0] neg_hi:[1,0,0]
	v_add_f32_e32 v150, v147, v146
	v_add_f32_e32 v151, v148, v149
	v_add_f32_e32 v175, v151, v150
	ds_read_b128 v[112:115], v197 offset:896
	ds_read_b128 v[116:119], v197 offset:912
	ds_read_b128 v[120:123], v197 offset:928
	ds_read_b128 v[124:127], v197 offset:944
	ds_read_b128 v[130:133], v197 offset:960
	ds_read_b128 v[134:137], v197 offset:976
	ds_read_b128 v[138:141], v197 offset:992
	s_waitcnt lgkmcnt(14)
	ds_read_b128 v[142:145], v197 offset:1008
	s_waitcnt lgkmcnt(12)
	v_pk_fma_f32 v[146:147], v[80:81], v[64:65], v[200:201] neg_lo:[1,0,0] neg_hi:[1,0,0]
	v_pk_fma_f32 v[148:149], v[82:83], v[66:67], v[200:201] neg_lo:[1,0,0] neg_hi:[1,0,0]
	v_pk_fma_f32 v[146:147], v[84:85], v[68:69], v[146:147] neg_lo:[1,0,0] neg_hi:[1,0,0]
	v_pk_fma_f32 v[148:149], v[86:87], v[70:71], v[148:149] neg_lo:[1,0,0] neg_hi:[1,0,0]
	v_pk_fma_f32 v[146:147], v[88:89], v[72:73], v[146:147] neg_lo:[1,0,0] neg_hi:[1,0,0]
	v_pk_fma_f32 v[148:149], v[90:91], v[74:75], v[148:149] neg_lo:[1,0,0] neg_hi:[1,0,0]
	v_pk_fma_f32 v[146:147], v[92:93], v[76:77], v[146:147] neg_lo:[1,0,0] neg_hi:[1,0,0]
	v_pk_fma_f32 v[148:149], v[94:95], v[78:79], v[148:149] neg_lo:[1,0,0] neg_hi:[1,0,0]
	s_waitcnt lgkmcnt(8)
	v_pk_fma_f32 v[146:147], v[96:97], v[154:155], v[146:147] neg_lo:[1,0,0] neg_hi:[1,0,0]
	v_pk_fma_f32 v[148:149], v[98:99], v[156:157], v[148:149] neg_lo:[1,0,0] neg_hi:[1,0,0]
	v_pk_fma_f32 v[146:147], v[100:101], v[158:159], v[146:147] neg_lo:[1,0,0] neg_hi:[1,0,0]
	v_pk_fma_f32 v[148:149], v[102:103], v[160:161], v[148:149] neg_lo:[1,0,0] neg_hi:[1,0,0]
	v_pk_fma_f32 v[146:147], v[104:105], v[162:163], v[146:147] neg_lo:[1,0,0] neg_hi:[1,0,0]
	v_pk_fma_f32 v[148:149], v[106:107], v[164:165], v[148:149] neg_lo:[1,0,0] neg_hi:[1,0,0]
	v_pk_fma_f32 v[146:147], v[108:109], v[166:167], v[146:147] neg_lo:[1,0,0] neg_hi:[1,0,0]
	v_pk_fma_f32 v[148:149], v[110:111], v[168:169], v[148:149] neg_lo:[1,0,0] neg_hi:[1,0,0]
	v_add_f32_e32 v150, v147, v146
	v_add_f32_e32 v151, v148, v149
	v_add_f32_e32 v176, v151, v150
	ds_read_b128 v[80:83], v197 offset:1024
	ds_read_b128 v[84:87], v197 offset:1040
	ds_read_b128 v[88:91], v197 offset:1056
	ds_read_b128 v[92:95], v197 offset:1072
	ds_read_b128 v[96:99], v197 offset:1088
	ds_read_b128 v[100:103], v197 offset:1104
	ds_read_b128 v[104:107], v197 offset:1120
	s_waitcnt lgkmcnt(14)
	ds_read_b128 v[108:111], v197 offset:1136
	s_waitcnt lgkmcnt(12)
	v_pk_fma_f32 v[146:147], v[112:113], v[64:65], v[200:201] neg_lo:[1,0,0] neg_hi:[1,0,0]
	v_pk_fma_f32 v[148:149], v[114:115], v[66:67], v[200:201] neg_lo:[1,0,0] neg_hi:[1,0,0]
	v_pk_fma_f32 v[146:147], v[116:117], v[68:69], v[146:147] neg_lo:[1,0,0] neg_hi:[1,0,0]
	v_pk_fma_f32 v[148:149], v[118:119], v[70:71], v[148:149] neg_lo:[1,0,0] neg_hi:[1,0,0]
	v_pk_fma_f32 v[146:147], v[120:121], v[72:73], v[146:147] neg_lo:[1,0,0] neg_hi:[1,0,0]
	v_pk_fma_f32 v[148:149], v[122:123], v[74:75], v[148:149] neg_lo:[1,0,0] neg_hi:[1,0,0]
	v_pk_fma_f32 v[146:147], v[124:125], v[76:77], v[146:147] neg_lo:[1,0,0] neg_hi:[1,0,0]
	v_pk_fma_f32 v[148:149], v[126:127], v[78:79], v[148:149] neg_lo:[1,0,0] neg_hi:[1,0,0]
	s_waitcnt lgkmcnt(8)
	v_pk_fma_f32 v[146:147], v[130:131], v[154:155], v[146:147] neg_lo:[1,0,0] neg_hi:[1,0,0]
	v_pk_fma_f32 v[148:149], v[132:133], v[156:157], v[148:149] neg_lo:[1,0,0] neg_hi:[1,0,0]
	v_pk_fma_f32 v[146:147], v[134:135], v[158:159], v[146:147] neg_lo:[1,0,0] neg_hi:[1,0,0]
	v_pk_fma_f32 v[148:149], v[136:137], v[160:161], v[148:149] neg_lo:[1,0,0] neg_hi:[1,0,0]
	v_pk_fma_f32 v[146:147], v[138:139], v[162:163], v[146:147] neg_lo:[1,0,0] neg_hi:[1,0,0]
	v_pk_fma_f32 v[148:149], v[140:141], v[164:165], v[148:149] neg_lo:[1,0,0] neg_hi:[1,0,0]
	v_pk_fma_f32 v[146:147], v[142:143], v[166:167], v[146:147] neg_lo:[1,0,0] neg_hi:[1,0,0]
	v_pk_fma_f32 v[148:149], v[144:145], v[168:169], v[148:149] neg_lo:[1,0,0] neg_hi:[1,0,0]
	v_add_f32_e32 v150, v147, v146
	v_add_f32_e32 v151, v148, v149
	v_add_f32_e32 v177, v151, v150
	ds_read_b128 v[112:115], v197 offset:1152
	ds_read_b128 v[116:119], v197 offset:1168
	ds_read_b128 v[120:123], v197 offset:1184
	ds_read_b128 v[124:127], v197 offset:1200
	ds_read_b128 v[130:133], v197 offset:1216
	ds_read_b128 v[134:137], v197 offset:1232
	ds_read_b128 v[138:141], v197 offset:1248
	s_waitcnt lgkmcnt(14)
	ds_read_b128 v[142:145], v197 offset:1264
	s_waitcnt lgkmcnt(12)
	v_pk_fma_f32 v[146:147], v[80:81], v[64:65], v[200:201] neg_lo:[1,0,0] neg_hi:[1,0,0]
	v_pk_fma_f32 v[148:149], v[82:83], v[66:67], v[200:201] neg_lo:[1,0,0] neg_hi:[1,0,0]
	v_pk_fma_f32 v[146:147], v[84:85], v[68:69], v[146:147] neg_lo:[1,0,0] neg_hi:[1,0,0]
	v_pk_fma_f32 v[148:149], v[86:87], v[70:71], v[148:149] neg_lo:[1,0,0] neg_hi:[1,0,0]
	v_pk_fma_f32 v[146:147], v[88:89], v[72:73], v[146:147] neg_lo:[1,0,0] neg_hi:[1,0,0]
	v_pk_fma_f32 v[148:149], v[90:91], v[74:75], v[148:149] neg_lo:[1,0,0] neg_hi:[1,0,0]
	v_pk_fma_f32 v[146:147], v[92:93], v[76:77], v[146:147] neg_lo:[1,0,0] neg_hi:[1,0,0]
	v_pk_fma_f32 v[148:149], v[94:95], v[78:79], v[148:149] neg_lo:[1,0,0] neg_hi:[1,0,0]
	s_waitcnt lgkmcnt(8)
	v_pk_fma_f32 v[146:147], v[96:97], v[154:155], v[146:147] neg_lo:[1,0,0] neg_hi:[1,0,0]
	v_pk_fma_f32 v[148:149], v[98:99], v[156:157], v[148:149] neg_lo:[1,0,0] neg_hi:[1,0,0]
	v_pk_fma_f32 v[146:147], v[100:101], v[158:159], v[146:147] neg_lo:[1,0,0] neg_hi:[1,0,0]
	v_pk_fma_f32 v[148:149], v[102:103], v[160:161], v[148:149] neg_lo:[1,0,0] neg_hi:[1,0,0]
	v_pk_fma_f32 v[146:147], v[104:105], v[162:163], v[146:147] neg_lo:[1,0,0] neg_hi:[1,0,0]
	v_pk_fma_f32 v[148:149], v[106:107], v[164:165], v[148:149] neg_lo:[1,0,0] neg_hi:[1,0,0]
	v_pk_fma_f32 v[146:147], v[108:109], v[166:167], v[146:147] neg_lo:[1,0,0] neg_hi:[1,0,0]
	v_pk_fma_f32 v[148:149], v[110:111], v[168:169], v[148:149] neg_lo:[1,0,0] neg_hi:[1,0,0]
	v_add_f32_e32 v150, v147, v146
	v_add_f32_e32 v151, v148, v149
	v_add_f32_e32 v178, v151, v150
	ds_read_b128 v[80:83], v197 offset:1280
	ds_read_b128 v[84:87], v197 offset:1296
	ds_read_b128 v[88:91], v197 offset:1312
	ds_read_b128 v[92:95], v197 offset:1328
	ds_read_b128 v[96:99], v197 offset:1344
	ds_read_b128 v[100:103], v197 offset:1360
	ds_read_b128 v[104:107], v197 offset:1376
	s_waitcnt lgkmcnt(14)
	ds_read_b128 v[108:111], v197 offset:1392
	s_waitcnt lgkmcnt(12)
	v_pk_fma_f32 v[146:147], v[112:113], v[64:65], v[200:201] neg_lo:[1,0,0] neg_hi:[1,0,0]
	v_pk_fma_f32 v[148:149], v[114:115], v[66:67], v[200:201] neg_lo:[1,0,0] neg_hi:[1,0,0]
	v_pk_fma_f32 v[146:147], v[116:117], v[68:69], v[146:147] neg_lo:[1,0,0] neg_hi:[1,0,0]
	v_pk_fma_f32 v[148:149], v[118:119], v[70:71], v[148:149] neg_lo:[1,0,0] neg_hi:[1,0,0]
	v_pk_fma_f32 v[146:147], v[120:121], v[72:73], v[146:147] neg_lo:[1,0,0] neg_hi:[1,0,0]
	v_pk_fma_f32 v[148:149], v[122:123], v[74:75], v[148:149] neg_lo:[1,0,0] neg_hi:[1,0,0]
	v_pk_fma_f32 v[146:147], v[124:125], v[76:77], v[146:147] neg_lo:[1,0,0] neg_hi:[1,0,0]
	v_pk_fma_f32 v[148:149], v[126:127], v[78:79], v[148:149] neg_lo:[1,0,0] neg_hi:[1,0,0]
	s_waitcnt lgkmcnt(8)
	v_pk_fma_f32 v[146:147], v[130:131], v[154:155], v[146:147] neg_lo:[1,0,0] neg_hi:[1,0,0]
	v_pk_fma_f32 v[148:149], v[132:133], v[156:157], v[148:149] neg_lo:[1,0,0] neg_hi:[1,0,0]
	v_pk_fma_f32 v[146:147], v[134:135], v[158:159], v[146:147] neg_lo:[1,0,0] neg_hi:[1,0,0]
	v_pk_fma_f32 v[148:149], v[136:137], v[160:161], v[148:149] neg_lo:[1,0,0] neg_hi:[1,0,0]
	v_pk_fma_f32 v[146:147], v[138:139], v[162:163], v[146:147] neg_lo:[1,0,0] neg_hi:[1,0,0]
	v_pk_fma_f32 v[148:149], v[140:141], v[164:165], v[148:149] neg_lo:[1,0,0] neg_hi:[1,0,0]
	v_pk_fma_f32 v[146:147], v[142:143], v[166:167], v[146:147] neg_lo:[1,0,0] neg_hi:[1,0,0]
	v_pk_fma_f32 v[148:149], v[144:145], v[168:169], v[148:149] neg_lo:[1,0,0] neg_hi:[1,0,0]
	v_add_f32_e32 v150, v147, v146
	v_add_f32_e32 v151, v148, v149
	v_add_f32_e32 v179, v151, v150
	ds_read_b128 v[112:115], v197 offset:1408
	ds_read_b128 v[116:119], v197 offset:1424
	ds_read_b128 v[120:123], v197 offset:1440
	ds_read_b128 v[124:127], v197 offset:1456
	ds_read_b128 v[130:133], v197 offset:1472
	ds_read_b128 v[134:137], v197 offset:1488
	ds_read_b128 v[138:141], v197 offset:1504
	s_waitcnt lgkmcnt(14)
	ds_read_b128 v[142:145], v197 offset:1520
	s_waitcnt lgkmcnt(12)
	v_pk_fma_f32 v[146:147], v[80:81], v[64:65], v[200:201] neg_lo:[1,0,0] neg_hi:[1,0,0]
	v_pk_fma_f32 v[148:149], v[82:83], v[66:67], v[200:201] neg_lo:[1,0,0] neg_hi:[1,0,0]
	v_pk_fma_f32 v[146:147], v[84:85], v[68:69], v[146:147] neg_lo:[1,0,0] neg_hi:[1,0,0]
	v_pk_fma_f32 v[148:149], v[86:87], v[70:71], v[148:149] neg_lo:[1,0,0] neg_hi:[1,0,0]
	v_pk_fma_f32 v[146:147], v[88:89], v[72:73], v[146:147] neg_lo:[1,0,0] neg_hi:[1,0,0]
	v_pk_fma_f32 v[148:149], v[90:91], v[74:75], v[148:149] neg_lo:[1,0,0] neg_hi:[1,0,0]
	v_pk_fma_f32 v[146:147], v[92:93], v[76:77], v[146:147] neg_lo:[1,0,0] neg_hi:[1,0,0]
	v_pk_fma_f32 v[148:149], v[94:95], v[78:79], v[148:149] neg_lo:[1,0,0] neg_hi:[1,0,0]
	s_waitcnt lgkmcnt(8)
	v_pk_fma_f32 v[146:147], v[96:97], v[154:155], v[146:147] neg_lo:[1,0,0] neg_hi:[1,0,0]
	v_pk_fma_f32 v[148:149], v[98:99], v[156:157], v[148:149] neg_lo:[1,0,0] neg_hi:[1,0,0]
	v_pk_fma_f32 v[146:147], v[100:101], v[158:159], v[146:147] neg_lo:[1,0,0] neg_hi:[1,0,0]
	v_pk_fma_f32 v[148:149], v[102:103], v[160:161], v[148:149] neg_lo:[1,0,0] neg_hi:[1,0,0]
	v_pk_fma_f32 v[146:147], v[104:105], v[162:163], v[146:147] neg_lo:[1,0,0] neg_hi:[1,0,0]
	v_pk_fma_f32 v[148:149], v[106:107], v[164:165], v[148:149] neg_lo:[1,0,0] neg_hi:[1,0,0]
	v_pk_fma_f32 v[146:147], v[108:109], v[166:167], v[146:147] neg_lo:[1,0,0] neg_hi:[1,0,0]
	v_pk_fma_f32 v[148:149], v[110:111], v[168:169], v[148:149] neg_lo:[1,0,0] neg_hi:[1,0,0]
	v_add_f32_e32 v150, v147, v146
	v_add_f32_e32 v151, v148, v149
	v_add_f32_e32 v180, v151, v150
	ds_read_b128 v[80:83], v197 offset:1536
	ds_read_b128 v[84:87], v197 offset:1552
	ds_read_b128 v[88:91], v197 offset:1568
	ds_read_b128 v[92:95], v197 offset:1584
	ds_read_b128 v[96:99], v197 offset:1600
	ds_read_b128 v[100:103], v197 offset:1616
	ds_read_b128 v[104:107], v197 offset:1632
	s_waitcnt lgkmcnt(14)
	ds_read_b128 v[108:111], v197 offset:1648
	s_waitcnt lgkmcnt(12)
	v_pk_fma_f32 v[146:147], v[112:113], v[64:65], v[200:201] neg_lo:[1,0,0] neg_hi:[1,0,0]
	v_pk_fma_f32 v[148:149], v[114:115], v[66:67], v[200:201] neg_lo:[1,0,0] neg_hi:[1,0,0]
	v_pk_fma_f32 v[146:147], v[116:117], v[68:69], v[146:147] neg_lo:[1,0,0] neg_hi:[1,0,0]
	v_pk_fma_f32 v[148:149], v[118:119], v[70:71], v[148:149] neg_lo:[1,0,0] neg_hi:[1,0,0]
	v_pk_fma_f32 v[146:147], v[120:121], v[72:73], v[146:147] neg_lo:[1,0,0] neg_hi:[1,0,0]
	v_pk_fma_f32 v[148:149], v[122:123], v[74:75], v[148:149] neg_lo:[1,0,0] neg_hi:[1,0,0]
	v_pk_fma_f32 v[146:147], v[124:125], v[76:77], v[146:147] neg_lo:[1,0,0] neg_hi:[1,0,0]
	v_pk_fma_f32 v[148:149], v[126:127], v[78:79], v[148:149] neg_lo:[1,0,0] neg_hi:[1,0,0]
	s_waitcnt lgkmcnt(8)
	v_pk_fma_f32 v[146:147], v[130:131], v[154:155], v[146:147] neg_lo:[1,0,0] neg_hi:[1,0,0]
	v_pk_fma_f32 v[148:149], v[132:133], v[156:157], v[148:149] neg_lo:[1,0,0] neg_hi:[1,0,0]
	v_pk_fma_f32 v[146:147], v[134:135], v[158:159], v[146:147] neg_lo:[1,0,0] neg_hi:[1,0,0]
	v_pk_fma_f32 v[148:149], v[136:137], v[160:161], v[148:149] neg_lo:[1,0,0] neg_hi:[1,0,0]
	v_pk_fma_f32 v[146:147], v[138:139], v[162:163], v[146:147] neg_lo:[1,0,0] neg_hi:[1,0,0]
	v_pk_fma_f32 v[148:149], v[140:141], v[164:165], v[148:149] neg_lo:[1,0,0] neg_hi:[1,0,0]
	v_pk_fma_f32 v[146:147], v[142:143], v[166:167], v[146:147] neg_lo:[1,0,0] neg_hi:[1,0,0]
	v_pk_fma_f32 v[148:149], v[144:145], v[168:169], v[148:149] neg_lo:[1,0,0] neg_hi:[1,0,0]
	v_add_f32_e32 v150, v147, v146
	v_add_f32_e32 v151, v148, v149
	v_add_f32_e32 v181, v151, v150
	ds_read_b128 v[112:115], v197 offset:1664
	ds_read_b128 v[116:119], v197 offset:1680
	ds_read_b128 v[120:123], v197 offset:1696
	ds_read_b128 v[124:127], v197 offset:1712
	ds_read_b128 v[130:133], v197 offset:1728
	ds_read_b128 v[134:137], v197 offset:1744
	ds_read_b128 v[138:141], v197 offset:1760
	s_waitcnt lgkmcnt(14)
	ds_read_b128 v[142:145], v197 offset:1776
	s_waitcnt lgkmcnt(12)
	v_pk_fma_f32 v[146:147], v[80:81], v[64:65], v[200:201] neg_lo:[1,0,0] neg_hi:[1,0,0]
	v_pk_fma_f32 v[148:149], v[82:83], v[66:67], v[200:201] neg_lo:[1,0,0] neg_hi:[1,0,0]
	v_pk_fma_f32 v[146:147], v[84:85], v[68:69], v[146:147] neg_lo:[1,0,0] neg_hi:[1,0,0]
	v_pk_fma_f32 v[148:149], v[86:87], v[70:71], v[148:149] neg_lo:[1,0,0] neg_hi:[1,0,0]
	v_pk_fma_f32 v[146:147], v[88:89], v[72:73], v[146:147] neg_lo:[1,0,0] neg_hi:[1,0,0]
	v_pk_fma_f32 v[148:149], v[90:91], v[74:75], v[148:149] neg_lo:[1,0,0] neg_hi:[1,0,0]
	v_pk_fma_f32 v[146:147], v[92:93], v[76:77], v[146:147] neg_lo:[1,0,0] neg_hi:[1,0,0]
	v_pk_fma_f32 v[148:149], v[94:95], v[78:79], v[148:149] neg_lo:[1,0,0] neg_hi:[1,0,0]
	s_waitcnt lgkmcnt(8)
	v_pk_fma_f32 v[146:147], v[96:97], v[154:155], v[146:147] neg_lo:[1,0,0] neg_hi:[1,0,0]
	v_pk_fma_f32 v[148:149], v[98:99], v[156:157], v[148:149] neg_lo:[1,0,0] neg_hi:[1,0,0]
	v_pk_fma_f32 v[146:147], v[100:101], v[158:159], v[146:147] neg_lo:[1,0,0] neg_hi:[1,0,0]
	v_pk_fma_f32 v[148:149], v[102:103], v[160:161], v[148:149] neg_lo:[1,0,0] neg_hi:[1,0,0]
	v_pk_fma_f32 v[146:147], v[104:105], v[162:163], v[146:147] neg_lo:[1,0,0] neg_hi:[1,0,0]
	v_pk_fma_f32 v[148:149], v[106:107], v[164:165], v[148:149] neg_lo:[1,0,0] neg_hi:[1,0,0]
	v_pk_fma_f32 v[146:147], v[108:109], v[166:167], v[146:147] neg_lo:[1,0,0] neg_hi:[1,0,0]
	v_pk_fma_f32 v[148:149], v[110:111], v[168:169], v[148:149] neg_lo:[1,0,0] neg_hi:[1,0,0]
	v_add_f32_e32 v150, v147, v146
	v_add_f32_e32 v151, v148, v149
	v_add_f32_e32 v182, v151, v150
	ds_read_b128 v[80:83], v197 offset:1792
	ds_read_b128 v[84:87], v197 offset:1808
	ds_read_b128 v[88:91], v197 offset:1824
	ds_read_b128 v[92:95], v197 offset:1840
	ds_read_b128 v[96:99], v197 offset:1856
	ds_read_b128 v[100:103], v197 offset:1872
	ds_read_b128 v[104:107], v197 offset:1888
	s_waitcnt lgkmcnt(14)
	ds_read_b128 v[108:111], v197 offset:1904
	s_waitcnt lgkmcnt(12)
	v_pk_fma_f32 v[146:147], v[112:113], v[64:65], v[200:201] neg_lo:[1,0,0] neg_hi:[1,0,0]
	v_pk_fma_f32 v[148:149], v[114:115], v[66:67], v[200:201] neg_lo:[1,0,0] neg_hi:[1,0,0]
	v_pk_fma_f32 v[146:147], v[116:117], v[68:69], v[146:147] neg_lo:[1,0,0] neg_hi:[1,0,0]
	v_pk_fma_f32 v[148:149], v[118:119], v[70:71], v[148:149] neg_lo:[1,0,0] neg_hi:[1,0,0]
	v_pk_fma_f32 v[146:147], v[120:121], v[72:73], v[146:147] neg_lo:[1,0,0] neg_hi:[1,0,0]
	v_pk_fma_f32 v[148:149], v[122:123], v[74:75], v[148:149] neg_lo:[1,0,0] neg_hi:[1,0,0]
	v_pk_fma_f32 v[146:147], v[124:125], v[76:77], v[146:147] neg_lo:[1,0,0] neg_hi:[1,0,0]
	v_pk_fma_f32 v[148:149], v[126:127], v[78:79], v[148:149] neg_lo:[1,0,0] neg_hi:[1,0,0]
	s_waitcnt lgkmcnt(8)
	v_pk_fma_f32 v[146:147], v[130:131], v[154:155], v[146:147] neg_lo:[1,0,0] neg_hi:[1,0,0]
	v_pk_fma_f32 v[148:149], v[132:133], v[156:157], v[148:149] neg_lo:[1,0,0] neg_hi:[1,0,0]
	v_pk_fma_f32 v[146:147], v[134:135], v[158:159], v[146:147] neg_lo:[1,0,0] neg_hi:[1,0,0]
	v_pk_fma_f32 v[148:149], v[136:137], v[160:161], v[148:149] neg_lo:[1,0,0] neg_hi:[1,0,0]
	v_pk_fma_f32 v[146:147], v[138:139], v[162:163], v[146:147] neg_lo:[1,0,0] neg_hi:[1,0,0]
	v_pk_fma_f32 v[148:149], v[140:141], v[164:165], v[148:149] neg_lo:[1,0,0] neg_hi:[1,0,0]
	v_pk_fma_f32 v[146:147], v[142:143], v[166:167], v[146:147] neg_lo:[1,0,0] neg_hi:[1,0,0]
	v_pk_fma_f32 v[148:149], v[144:145], v[168:169], v[148:149] neg_lo:[1,0,0] neg_hi:[1,0,0]
	v_add_f32_e32 v150, v147, v146
	v_add_f32_e32 v151, v148, v149
	v_add_f32_e32 v183, v151, v150
	ds_read_b128 v[112:115], v197 offset:1920
	ds_read_b128 v[116:119], v197 offset:1936
	ds_read_b128 v[120:123], v197 offset:1952
	ds_read_b128 v[124:127], v197 offset:1968
	ds_read_b128 v[130:133], v197 offset:1984
	ds_read_b128 v[134:137], v197 offset:2000
	ds_read_b128 v[138:141], v197 offset:2016
	s_waitcnt lgkmcnt(14)
	ds_read_b128 v[142:145], v197 offset:2032
	s_waitcnt lgkmcnt(12)
	v_pk_fma_f32 v[146:147], v[80:81], v[64:65], v[200:201] neg_lo:[1,0,0] neg_hi:[1,0,0]
	v_pk_fma_f32 v[148:149], v[82:83], v[66:67], v[200:201] neg_lo:[1,0,0] neg_hi:[1,0,0]
	v_pk_fma_f32 v[146:147], v[84:85], v[68:69], v[146:147] neg_lo:[1,0,0] neg_hi:[1,0,0]
	v_pk_fma_f32 v[148:149], v[86:87], v[70:71], v[148:149] neg_lo:[1,0,0] neg_hi:[1,0,0]
	v_pk_fma_f32 v[146:147], v[88:89], v[72:73], v[146:147] neg_lo:[1,0,0] neg_hi:[1,0,0]
	v_pk_fma_f32 v[148:149], v[90:91], v[74:75], v[148:149] neg_lo:[1,0,0] neg_hi:[1,0,0]
	v_pk_fma_f32 v[146:147], v[92:93], v[76:77], v[146:147] neg_lo:[1,0,0] neg_hi:[1,0,0]
	v_pk_fma_f32 v[148:149], v[94:95], v[78:79], v[148:149] neg_lo:[1,0,0] neg_hi:[1,0,0]
	s_waitcnt lgkmcnt(8)
	v_pk_fma_f32 v[146:147], v[96:97], v[154:155], v[146:147] neg_lo:[1,0,0] neg_hi:[1,0,0]
	v_pk_fma_f32 v[148:149], v[98:99], v[156:157], v[148:149] neg_lo:[1,0,0] neg_hi:[1,0,0]
	v_pk_fma_f32 v[146:147], v[100:101], v[158:159], v[146:147] neg_lo:[1,0,0] neg_hi:[1,0,0]
	v_pk_fma_f32 v[148:149], v[102:103], v[160:161], v[148:149] neg_lo:[1,0,0] neg_hi:[1,0,0]
	v_pk_fma_f32 v[146:147], v[104:105], v[162:163], v[146:147] neg_lo:[1,0,0] neg_hi:[1,0,0]
	v_pk_fma_f32 v[148:149], v[106:107], v[164:165], v[148:149] neg_lo:[1,0,0] neg_hi:[1,0,0]
	v_pk_fma_f32 v[146:147], v[108:109], v[166:167], v[146:147] neg_lo:[1,0,0] neg_hi:[1,0,0]
	v_pk_fma_f32 v[148:149], v[110:111], v[168:169], v[148:149] neg_lo:[1,0,0] neg_hi:[1,0,0]
	v_add_f32_e32 v150, v147, v146
	v_add_f32_e32 v151, v148, v149
	v_add_f32_e32 v184, v151, v150
	s_waitcnt lgkmcnt(4)
	v_pk_fma_f32 v[146:147], v[112:113], v[64:65], v[200:201] neg_lo:[1,0,0] neg_hi:[1,0,0]
	v_pk_fma_f32 v[148:149], v[114:115], v[66:67], v[200:201] neg_lo:[1,0,0] neg_hi:[1,0,0]
	v_pk_fma_f32 v[146:147], v[116:117], v[68:69], v[146:147] neg_lo:[1,0,0] neg_hi:[1,0,0]
	v_pk_fma_f32 v[148:149], v[118:119], v[70:71], v[148:149] neg_lo:[1,0,0] neg_hi:[1,0,0]
	v_pk_fma_f32 v[146:147], v[120:121], v[72:73], v[146:147] neg_lo:[1,0,0] neg_hi:[1,0,0]
	v_pk_fma_f32 v[148:149], v[122:123], v[74:75], v[148:149] neg_lo:[1,0,0] neg_hi:[1,0,0]
	v_pk_fma_f32 v[146:147], v[124:125], v[76:77], v[146:147] neg_lo:[1,0,0] neg_hi:[1,0,0]
	v_pk_fma_f32 v[148:149], v[126:127], v[78:79], v[148:149] neg_lo:[1,0,0] neg_hi:[1,0,0]
	s_waitcnt lgkmcnt(0)
	v_pk_fma_f32 v[146:147], v[130:131], v[154:155], v[146:147] neg_lo:[1,0,0] neg_hi:[1,0,0]
	v_pk_fma_f32 v[148:149], v[132:133], v[156:157], v[148:149] neg_lo:[1,0,0] neg_hi:[1,0,0]
	v_pk_fma_f32 v[146:147], v[134:135], v[158:159], v[146:147] neg_lo:[1,0,0] neg_hi:[1,0,0]
	v_pk_fma_f32 v[148:149], v[136:137], v[160:161], v[148:149] neg_lo:[1,0,0] neg_hi:[1,0,0]
	v_pk_fma_f32 v[146:147], v[138:139], v[162:163], v[146:147] neg_lo:[1,0,0] neg_hi:[1,0,0]
	v_pk_fma_f32 v[148:149], v[140:141], v[164:165], v[148:149] neg_lo:[1,0,0] neg_hi:[1,0,0]
	v_pk_fma_f32 v[146:147], v[142:143], v[166:167], v[146:147] neg_lo:[1,0,0] neg_hi:[1,0,0]
	v_pk_fma_f32 v[148:149], v[144:145], v[168:169], v[148:149] neg_lo:[1,0,0] neg_hi:[1,0,0]
	v_add_f32_e32 v150, v147, v146
	v_add_f32_e32 v151, v148, v149
	v_add_f32_e32 v185, v151, v150
	s_cmp_lg_u32 s87, 0
	s_cbranch_scc1 .Ltri2_wb_b
	v_add_u32_e32 v204, v195, v199
	v_add_u32_e32 v205, v196, v199
	ds_write_b32 v204, v0
	ds_write_b32 v204, v1 offset:272
	ds_write_b32 v204, v2 offset:544
	ds_write_b32 v204, v3 offset:816
	ds_write_b32 v204, v4 offset:1088
	ds_write_b32 v204, v5 offset:1360
	ds_write_b32 v204, v6 offset:1632
	ds_write_b32 v204, v7 offset:1904
	ds_write_b32 v204, v8 offset:2176
	ds_write_b32 v204, v9 offset:2448
	ds_write_b32 v204, v10 offset:2720
	ds_write_b32 v204, v11 offset:2992
	ds_write_b32 v204, v12 offset:3264
	ds_write_b32 v204, v13 offset:3536
	ds_write_b32 v204, v14 offset:3808
	ds_write_b32 v204, v15 offset:4080
	ds_write_b32 v204, v16 offset:4352
	ds_write_b32 v204, v17 offset:4624
	ds_write_b32 v204, v18 offset:4896
	ds_write_b32 v204, v19 offset:5168
	ds_write_b32 v204, v20 offset:5440
	ds_write_b32 v204, v21 offset:5712
	ds_write_b32 v204, v22 offset:5984
	ds_write_b32 v204, v23 offset:6256
	ds_write_b32 v204, v24 offset:6528
	ds_write_b32 v204, v25 offset:6800
	ds_write_b32 v204, v26 offset:7072
	ds_write_b32 v204, v27 offset:7344
	ds_write_b32 v204, v28 offset:7616
	ds_write_b32 v204, v29 offset:7888
	ds_write_b32 v204, v30 offset:8160
	ds_write_b32 v204, v31 offset:8432
	ds_write_b32 v205, v170
	ds_write_b32 v205, v171 offset:272
	ds_write_b32 v205, v172 offset:544
	ds_write_b32 v205, v173 offset:816
	ds_write_b32 v205, v174 offset:1088
	ds_write_b32 v205, v175 offset:1360
	ds_write_b32 v205, v176 offset:1632
	ds_write_b32 v205, v177 offset:1904
	ds_write_b32 v205, v178 offset:2176
	ds_write_b32 v205, v179 offset:2448
	ds_write_b32 v205, v180 offset:2720
	ds_write_b32 v205, v181 offset:2992
	ds_write_b32 v205, v182 offset:3264
	ds_write_b32 v205, v183 offset:3536
	ds_write_b32 v205, v184 offset:3808
	ds_write_b32 v205, v185 offset:4080
	s_branch .Ltri2_wb_done
.Ltri2_wb_b:
	v_sub_u32_e32 v150, 1, v189
	v_mul_u32_u24_e32 v151, 0x2200, v150
	v_lshlrev_b32_e32 v152, 7, v150
	v_sub_u32_e32 v153, 31, v188
	v_lshl_add_u32 v152, v153, 2, v152
	v_add3_u32 v204, v194, v151, v152
	ds_write_b32 v204, v0 offset:8432
	ds_write_b32 v204, v1 offset:8160
	ds_write_b32 v204, v2 offset:7888
	ds_write_b32 v204, v3 offset:7616
	ds_write_b32 v204, v4 offset:7344
	ds_write_b32 v204, v5 offset:7072
	ds_write_b32 v204, v6 offset:6800
	ds_write_b32 v204, v7 offset:6528
	ds_write_b32 v204, v8 offset:6256
	ds_write_b32 v204, v9 offset:5984
	ds_write_b32 v204, v10 offset:5712
	ds_write_b32 v204, v11 offset:5440
	ds_write_b32 v204, v12 offset:5168
	ds_write_b32 v204, v13 offset:4896
	ds_write_b32 v204, v14 offset:4624
	ds_write_b32 v204, v15 offset:4352
	ds_write_b32 v204, v16 offset:4080
	ds_write_b32 v204, v17 offset:3808
	ds_write_b32 v204, v18 offset:3536
	ds_write_b32 v204, v19 offset:3264
	ds_write_b32 v204, v20 offset:2992
	ds_write_b32 v204, v21 offset:2720
	ds_write_b32 v204, v22 offset:2448
	ds_write_b32 v204, v23 offset:2176
	ds_write_b32 v204, v24 offset:1904
	ds_write_b32 v204, v25 offset:1632
	ds_write_b32 v204, v26 offset:1360
	ds_write_b32 v204, v27 offset:1088
	ds_write_b32 v204, v28 offset:816
	ds_write_b32 v204, v29 offset:544
	ds_write_b32 v204, v30 offset:272
	ds_write_b32 v204, v31
	v_mul_u32_u24_e32 v151, 0x1100, v150
	v_sub_u32_e32 v153, 63, v188
	v_lshlrev_b32_e32 v153, 2, v153
	v_add3_u32 v205, v194, v151, v153
	ds_write_b32 v205, v170 offset:4080
	ds_write_b32 v205, v171 offset:3808
	ds_write_b32 v205, v172 offset:3536
	ds_write_b32 v205, v173 offset:3264
	ds_write_b32 v205, v174 offset:2992
	ds_write_b32 v205, v175 offset:2720
	ds_write_b32 v205, v176 offset:2448
	ds_write_b32 v205, v177 offset:2176
	ds_write_b32 v205, v178 offset:1904
	ds_write_b32 v205, v179 offset:1632
	ds_write_b32 v205, v180 offset:1360
	ds_write_b32 v205, v181 offset:1088
	ds_write_b32 v205, v182 offset:816
	ds_write_b32 v205, v183 offset:544
	ds_write_b32 v205, v184 offset:272
	ds_write_b32 v205, v185
	v_sub_u32_e32 v153, 31, v188
	v_lshlrev_b32_e32 v153, 2, v153
	v_add_u32_e32 v151, 0x2200, v151
	v_add3_u32 v204, v194, v151, v153
	ds_write_b32 v204, v200 offset:4080
	ds_write_b32 v204, v200 offset:3808
	ds_write_b32 v204, v200 offset:3536
	ds_write_b32 v204, v200 offset:3264
	ds_write_b32 v204, v200 offset:2992
	ds_write_b32 v204, v200 offset:2720
	ds_write_b32 v204, v200 offset:2448
	ds_write_b32 v204, v200 offset:2176
	ds_write_b32 v204, v200 offset:1904
	ds_write_b32 v204, v200 offset:1632
	ds_write_b32 v204, v200 offset:1360
	ds_write_b32 v204, v200 offset:1088
	ds_write_b32 v204, v200 offset:816
	ds_write_b32 v204, v200 offset:544
	ds_write_b32 v204, v200 offset:272
	ds_write_b32 v204, v200
.Ltri2_wb_done:
	s_add_i32 s0, s28, s86
	s_cmpk_lt_i32 s0, 0x900
	s_cselect_b32 s0, s0, s28
	s_mul_hi_i32 s1, s0, 0x2aaaaaab
	s_lshr_b32 s2, s1, 31
	s_ashr_i32 s1, s1, 1
	s_add_i32 s1, s1, s2
	s_mul_i32 s2, s1, -12
	s_add_i32 s2, s2, s0
	v_lshl_add_u32 v3, s1, 6, v187
	v_readlane_b32 s0, v253, 59
	v_readlane_b32 s1, v253, 60
	s_lshl_b32 s2, s2, 7
	v_mov_b64_e32 v[0:1], s[0:1]
	s_movk_i32 s0, 0x3800
	v_mad_i64_i32 v[0:1], s[0:1], v3, s0, v[0:1]
	s_ashr_i32 s3, s2, 31
	v_lshl_add_u64 v[0:1], s[2:3], 1, v[0:1]
	v_lshl_add_u64 v[0:1], v[0:1], 0, v[128:129]
	global_load_dwordx4 v[96:99], v[0:1], off offset:2064
	global_load_dwordx4 v[72:75], v[0:1], off offset:2048
	v_cmp_gt_i32_e32 vcc, s85, v3
	v_mov_b32_e32 v86, v129
	v_cndmask_b32_e32 v2, v240, v241, vcc
	v_mov_b32_e32 v87, v129
	v_and_b32_e32 v3, v2, v3
	s_mov_b64 s[0:1], 0x800
	v_mov_b32_e32 v84, v129
	v_mov_b32_e32 v85, v129
	v_mov_b64_e32 v[90:91], v[86:87]
	v_mov_b64_e32 v[106:107], v[86:87]
	v_cmp_ne_u32_e64 s[38:39], 0, v3
	v_lshl_add_u64 v[0:1], v[0:1], 0, s[0:1]
	v_mov_b64_e32 v[88:89], v[84:85]
	v_mov_b64_e32 v[104:105], v[84:85]
	s_and_saveexec_b64 s[10:11], s[38:39]
	s_cbranch_execz .LBB0_285
	s_movk_i32 s0, 0xc800
	v_add_co_u32_e32 v6, vcc, 0xffffd000, v0
	s_mov_b32 s1, -1
	s_nop 0
	v_addc_co_u32_e32 v7, vcc, -1, v1, vcc
	v_lshl_add_u64 v[4:5], v[0:1], 0, s[0:1]
	global_load_dwordx4 v[88:91], v[6:7], off offset:-2048
	global_load_dwordx4 v[104:107], v[4:5], off offset:16
